# P1 epilogue rewritten: one kind dispatch per unit, straight-line packed-f32 code, SGPR-base stores
# speedup vs baseline: 1.0165x; 1.0165x over previous
; __device__ __forceinline__ float sigm(float x) { return __builtin_amdgcn_rcpf(1.f + __expf(-x)); }
; __device__ __forceinline__ u32x4 pack8(const f32x4 v0, const f32x4 v1) { u32x4 w; w.x = cvt_pk_bf16(v0[0], v0[1]); w.y = cvt_pk_bf16(v0[2], v0[3]); w.z = cvt_pk_bf16(v1[0], v1[1]); w.w = cvt_pk_bf16(v1[2], v1[3]); return w; }
;     __device__ __forceinline__ void operator()(f32x4 (&acc)[2][2][4][2], const Unit& u, int wr, int wc, int fr, int fq) const {
;     ...
;         const int pn = u.pn;
;         {
;             const int kind = ((pn >= 4 && pn < 8) || (pn >= 20 && pn < 24) || (pn >= 28 && pn < 32)) ? 1 : (pn >= 8 && pn < 12) ? 2 : (pn >= 32) ? 3 : 0;
;             bf16_t* base = u.O + (size_t)(wr * 64 + fr) * LDZ + wc * 32 + 8 * fq;
;             f32x4 bv[2][2];
; #pragma unroll
;             for (int bj = 0; bj < 2; ++bj)
; #pragma unroll
;                 for (int n = 0; n < 2; ++n) bv[bj][n] = (kind == 3) ? *(const f32x4*)(b_merge + (pn * 256 - 8192) + wc * 32 + 8 * fq + bj * HALF + 4 * n) : (f32x4){0.f, 0.f, 0.f, 0.f};
; #pragma unroll
;             for (int ai = 0; ai < 2; ++ai)
; #pragma unroll
;                 for (int m = 0; m < 4; ++m) { bf16_t* rowp = base + (size_t)(ai * HALF + m * 16) * LDZ;
; #pragma unroll
;                     for (int bj = 0; bj < 2; ++bj) { f32x4 v0 = acc[ai][bj][m][0], v1 = acc[ai][bj][m][1];
;                         if (kind == 1) {
; #pragma unroll
;                             for (int e = 0; e < 4; ++e) { v0[e] = v0[e] * sigm(v0[e]); v1[e] = v1[e] * sigm(v1[e]); } }
;                         else if (kind == 2) { v0 = v0 * (0.125f * LOG2E); v1 = v1 * (0.125f * LOG2E); }
;                         else if (kind == 3) {
; #pragma unroll
;                             for (int e = 0; e < 4; ++e) { v0[e] = sigm(v0[e] + bv[bj][0][e]); v1[e] = sigm(v1[e] + bv[bj][1][e]); } }
;                         __builtin_nontemporal_store(pack8(v0, v1), (u32x4*)(rowp + bj * HALF)); } }
.LBB0_174:
	v_add_u32_e32 v138, s64, v166
	v_lshlrev_b32_e32 v138, 11, v138
	v_lshl_add_u32 v138, v167, 4, v138
	s_lshl_b32 s2, s65, 1
	v_add_u32_e32 v138, s2, v138
	s_cmp_lg_u32 s39, 3
	s_cbranch_scc1 .Lepi1_nob
	s_lshl_b32 s6, s56, 10
	s_add_u32 s6, s8, s6
	s_addc_u32 s7, s9, 0
	s_add_u32 s6, s6, s73
	s_addc_u32 s7, s7, 0
	s_add_u32 s6, s6, 0xffff8000
	s_addc_u32 s7, s7, -1
	v_lshlrev_b32_e32 v139, 5, v167
	global_load_dwordx4 v[202:205], v139, s[6:7]
	global_load_dwordx4 v[206:209], v139, s[6:7] offset:16
	global_load_dwordx4 v[210:213], v139, s[6:7] offset:512
	global_load_dwordx4 v[214:217], v139, s[6:7] offset:528
	s_waitcnt vmcnt(0)
	s_branch .Lepi1_k3
.Lepi1_nob:
	s_cmp_eq_u32 s39, 0
	s_cbranch_scc1 .Lepi1_k0
	s_cmp_eq_u32 s39, 1
	s_cbranch_scc1 .Lepi1_k1
	s_branch .Lepi1_k2
.Lepi1_k0:
	s_mov_b64 s[6:7], s[50:51]
	v_cvt_pk_bf16_f32 v130, v126, v127
	v_cvt_pk_bf16_f32 v131, v128, v129
	v_cvt_pk_bf16_f32 v132, v122, v123
	v_cvt_pk_bf16_f32 v133, v124, v125
	global_store_dwordx4 v138, v[130:133], s[6:7] nt
	v_cvt_pk_bf16_f32 v134, v62, v63
	v_cvt_pk_bf16_f32 v135, v64, v65
	v_cvt_pk_bf16_f32 v136, v58, v59
	v_cvt_pk_bf16_f32 v137, v60, v61
	global_store_dwordx4 v138, v[134:137], s[6:7] offset:256 nt
	s_add_u32 s6, s6, 0x8000
	s_addc_u32 s7, s7, 0
	v_cvt_pk_bf16_f32 v140, v118, v119
	v_cvt_pk_bf16_f32 v141, v120, v121
	v_cvt_pk_bf16_f32 v142, v114, v115
	v_cvt_pk_bf16_f32 v143, v116, v117
	global_store_dwordx4 v138, v[140:143], s[6:7] nt
	v_cvt_pk_bf16_f32 v156, v54, v55
	v_cvt_pk_bf16_f32 v157, v56, v57
	v_cvt_pk_bf16_f32 v158, v50, v51
	v_cvt_pk_bf16_f32 v159, v52, v53
	global_store_dwordx4 v138, v[156:159], s[6:7] offset:256 nt
	s_add_u32 s6, s6, 0x8000
	s_addc_u32 s7, s7, 0
	v_cvt_pk_bf16_f32 v130, v110, v111
	v_cvt_pk_bf16_f32 v131, v112, v113
	v_cvt_pk_bf16_f32 v132, v106, v107
	v_cvt_pk_bf16_f32 v133, v108, v109
	global_store_dwordx4 v138, v[130:133], s[6:7] nt
	v_cvt_pk_bf16_f32 v134, v46, v47
	v_cvt_pk_bf16_f32 v135, v48, v49
	v_cvt_pk_bf16_f32 v136, v42, v43
	v_cvt_pk_bf16_f32 v137, v44, v45
	global_store_dwordx4 v138, v[134:137], s[6:7] offset:256 nt
	s_add_u32 s6, s6, 0x8000
	s_addc_u32 s7, s7, 0
	v_cvt_pk_bf16_f32 v140, v102, v103
	v_cvt_pk_bf16_f32 v141, v104, v105
	v_cvt_pk_bf16_f32 v142, v98, v99
	v_cvt_pk_bf16_f32 v143, v100, v101
	global_store_dwordx4 v138, v[140:143], s[6:7] nt
	v_cvt_pk_bf16_f32 v156, v38, v39
	v_cvt_pk_bf16_f32 v157, v40, v41
	v_cvt_pk_bf16_f32 v158, v34, v35
	v_cvt_pk_bf16_f32 v159, v36, v37
	global_store_dwordx4 v138, v[156:159], s[6:7] offset:256 nt
	s_add_u32 s6, s6, 0x28000
	s_addc_u32 s7, s7, 0
	v_cvt_pk_bf16_f32 v130, v94, v95
	v_cvt_pk_bf16_f32 v131, v96, v97
	v_cvt_pk_bf16_f32 v132, v90, v91
	v_cvt_pk_bf16_f32 v133, v92, v93
	global_store_dwordx4 v138, v[130:133], s[6:7] nt
	v_cvt_pk_bf16_f32 v134, v30, v31
	v_cvt_pk_bf16_f32 v135, v32, v33
	v_cvt_pk_bf16_f32 v136, v26, v27
	v_cvt_pk_bf16_f32 v137, v28, v29
	global_store_dwordx4 v138, v[134:137], s[6:7] offset:256 nt
	s_add_u32 s6, s6, 0x8000
	s_addc_u32 s7, s7, 0
	v_cvt_pk_bf16_f32 v140, v86, v87
	v_cvt_pk_bf16_f32 v141, v88, v89
	v_cvt_pk_bf16_f32 v142, v82, v83
	v_cvt_pk_bf16_f32 v143, v84, v85
	global_store_dwordx4 v138, v[140:143], s[6:7] nt
	v_cvt_pk_bf16_f32 v156, v22, v23
	v_cvt_pk_bf16_f32 v157, v24, v25
	v_cvt_pk_bf16_f32 v158, v18, v19
	v_cvt_pk_bf16_f32 v159, v20, v21
	global_store_dwordx4 v138, v[156:159], s[6:7] offset:256 nt
	s_add_u32 s6, s6, 0x8000
	s_addc_u32 s7, s7, 0
	v_cvt_pk_bf16_f32 v130, v78, v79
	v_cvt_pk_bf16_f32 v131, v80, v81
	v_cvt_pk_bf16_f32 v132, v74, v75
	v_cvt_pk_bf16_f32 v133, v76, v77
	global_store_dwordx4 v138, v[130:133], s[6:7] nt
	v_cvt_pk_bf16_f32 v134, v14, v15
	v_cvt_pk_bf16_f32 v135, v16, v17
	v_cvt_pk_bf16_f32 v136, v10, v11
	v_cvt_pk_bf16_f32 v137, v12, v13
	global_store_dwordx4 v138, v[134:137], s[6:7] offset:256 nt
	s_add_u32 s6, s6, 0x8000
	s_addc_u32 s7, s7, 0
	v_cvt_pk_bf16_f32 v140, v70, v71
	v_cvt_pk_bf16_f32 v141, v72, v73
	v_cvt_pk_bf16_f32 v142, v66, v67
	v_cvt_pk_bf16_f32 v143, v68, v69
	global_store_dwordx4 v138, v[140:143], s[6:7] nt
	v_cvt_pk_bf16_f32 v156, v6, v7
	v_cvt_pk_bf16_f32 v157, v8, v9
	v_cvt_pk_bf16_f32 v158, v2, v3
	v_cvt_pk_bf16_f32 v159, v4, v5
	global_store_dwordx4 v138, v[156:159], s[6:7] offset:256 nt
	s_branch .Lepi1_done
; __device__ __forceinline__ float sigm(float x) { return __builtin_amdgcn_rcpf(1.f + __expf(-x)); }
; __device__ __forceinline__ u32x4 pack8(const f32x4 v0, const f32x4 v1) { u32x4 w; w.x = cvt_pk_bf16(v0[0], v0[1]); w.y = cvt_pk_bf16(v0[2], v0[3]); w.z = cvt_pk_bf16(v1[0], v1[1]); w.w = cvt_pk_bf16(v1[2], v1[3]); return w; }
;     __device__ __forceinline__ void operator()(f32x4 (&acc)[2][2][4][2], const Unit& u, int wr, int wc, int fr, int fq) const {
;     ...
;             for (int ai = 0; ai < 2; ++ai)
; #pragma unroll
;                 for (int m = 0; m < 4; ++m) { bf16_t* rowp = base + (size_t)(ai * HALF + m * 16) * LDZ;
; #pragma unroll
;                     for (int bj = 0; bj < 2; ++bj) { f32x4 v0 = acc[ai][bj][m][0], v1 = acc[ai][bj][m][1];
;                         if (kind == 1) {
; #pragma unroll
;                             for (int e = 0; e < 4; ++e) { v0[e] = v0[e] * sigm(v0[e]); v1[e] = v1[e] * sigm(v1[e]); } }
;                         else if (kind == 2) { v0 = v0 * (0.125f * LOG2E); v1 = v1 * (0.125f * LOG2E); }
;                         else if (kind == 3) {
; #pragma unroll
;                             for (int e = 0; e < 4; ++e) { v0[e] = sigm(v0[e] + bv[bj][0][e]); v1[e] = sigm(v1[e] + bv[bj][1][e]); } }
;                         __builtin_nontemporal_store(pack8(v0, v1), (u32x4*)(rowp + bj * HALF)); } }
.Lepi1_k1:
	s_mov_b64 s[6:7], s[50:51]
	v_pk_mul_f32 v[172:173], v[126:127], s[24:25] op_sel_hi:[1,0]
	v_pk_mul_f32 v[174:175], v[128:129], s[24:25] op_sel_hi:[1,0]
	v_pk_mul_f32 v[176:177], v[122:123], s[24:25] op_sel_hi:[1,0]
	v_pk_mul_f32 v[178:179], v[124:125], s[24:25] op_sel_hi:[1,0]
	v_exp_f32_e32 v172, v172
	v_exp_f32_e32 v173, v173
	v_exp_f32_e32 v174, v174
	v_exp_f32_e32 v175, v175
	v_exp_f32_e32 v176, v176
	v_exp_f32_e32 v177, v177
	v_exp_f32_e32 v178, v178
	v_exp_f32_e32 v179, v179
	v_pk_add_f32 v[172:173], v[172:173], 1.0 op_sel_hi:[1,0]
	v_pk_add_f32 v[174:175], v[174:175], 1.0 op_sel_hi:[1,0]
	v_pk_add_f32 v[176:177], v[176:177], 1.0 op_sel_hi:[1,0]
	v_pk_add_f32 v[178:179], v[178:179], 1.0 op_sel_hi:[1,0]
	v_rcp_f32_e32 v172, v172
	v_rcp_f32_e32 v173, v173
	v_rcp_f32_e32 v174, v174
	v_rcp_f32_e32 v175, v175
	v_rcp_f32_e32 v176, v176
	v_rcp_f32_e32 v177, v177
	v_rcp_f32_e32 v178, v178
	v_rcp_f32_e32 v179, v179
	v_pk_mul_f32 v[172:173], v[126:127], v[172:173]
	v_pk_mul_f32 v[174:175], v[128:129], v[174:175]
	v_pk_mul_f32 v[176:177], v[122:123], v[176:177]
	v_pk_mul_f32 v[178:179], v[124:125], v[178:179]
	v_cvt_pk_bf16_f32 v130, v172, v173
	v_cvt_pk_bf16_f32 v131, v174, v175
	v_cvt_pk_bf16_f32 v132, v176, v177
	v_cvt_pk_bf16_f32 v133, v178, v179
	global_store_dwordx4 v138, v[130:133], s[6:7] nt
	v_pk_mul_f32 v[180:181], v[62:63], s[24:25] op_sel_hi:[1,0]
	v_pk_mul_f32 v[182:183], v[64:65], s[24:25] op_sel_hi:[1,0]
	v_pk_mul_f32 v[184:185], v[58:59], s[24:25] op_sel_hi:[1,0]
	v_pk_mul_f32 v[186:187], v[60:61], s[24:25] op_sel_hi:[1,0]
	v_exp_f32_e32 v180, v180
	v_exp_f32_e32 v181, v181
	v_exp_f32_e32 v182, v182
	v_exp_f32_e32 v183, v183
	v_exp_f32_e32 v184, v184
	v_exp_f32_e32 v185, v185
	v_exp_f32_e32 v186, v186
	v_exp_f32_e32 v187, v187
	v_pk_add_f32 v[180:181], v[180:181], 1.0 op_sel_hi:[1,0]
	v_pk_add_f32 v[182:183], v[182:183], 1.0 op_sel_hi:[1,0]
	v_pk_add_f32 v[184:185], v[184:185], 1.0 op_sel_hi:[1,0]
	v_pk_add_f32 v[186:187], v[186:187], 1.0 op_sel_hi:[1,0]
	v_rcp_f32_e32 v180, v180
	v_rcp_f32_e32 v181, v181
	v_rcp_f32_e32 v182, v182
	v_rcp_f32_e32 v183, v183
	v_rcp_f32_e32 v184, v184
	v_rcp_f32_e32 v185, v185
	v_rcp_f32_e32 v186, v186
	v_rcp_f32_e32 v187, v187
	v_pk_mul_f32 v[180:181], v[62:63], v[180:181]
	v_pk_mul_f32 v[182:183], v[64:65], v[182:183]
	v_pk_mul_f32 v[184:185], v[58:59], v[184:185]
	v_pk_mul_f32 v[186:187], v[60:61], v[186:187]
	v_cvt_pk_bf16_f32 v134, v180, v181
	v_cvt_pk_bf16_f32 v135, v182, v183
	v_cvt_pk_bf16_f32 v136, v184, v185
	v_cvt_pk_bf16_f32 v137, v186, v187
	global_store_dwordx4 v138, v[134:137], s[6:7] offset:256 nt
	s_add_u32 s6, s6, 0x8000
	s_addc_u32 s7, s7, 0
	v_pk_mul_f32 v[172:173], v[118:119], s[24:25] op_sel_hi:[1,0]
	v_pk_mul_f32 v[174:175], v[120:121], s[24:25] op_sel_hi:[1,0]
	v_pk_mul_f32 v[176:177], v[114:115], s[24:25] op_sel_hi:[1,0]
	v_pk_mul_f32 v[178:179], v[116:117], s[24:25] op_sel_hi:[1,0]
	v_exp_f32_e32 v172, v172
	v_exp_f32_e32 v173, v173
	v_exp_f32_e32 v174, v174
	v_exp_f32_e32 v175, v175
	v_exp_f32_e32 v176, v176
	v_exp_f32_e32 v177, v177
	v_exp_f32_e32 v178, v178
	v_exp_f32_e32 v179, v179
	v_pk_add_f32 v[172:173], v[172:173], 1.0 op_sel_hi:[1,0]
	v_pk_add_f32 v[174:175], v[174:175], 1.0 op_sel_hi:[1,0]
	v_pk_add_f32 v[176:177], v[176:177], 1.0 op_sel_hi:[1,0]
	v_pk_add_f32 v[178:179], v[178:179], 1.0 op_sel_hi:[1,0]
	v_rcp_f32_e32 v172, v172
	v_rcp_f32_e32 v173, v173
	v_rcp_f32_e32 v174, v174
	v_rcp_f32_e32 v175, v175
	v_rcp_f32_e32 v176, v176
	v_rcp_f32_e32 v177, v177
	v_rcp_f32_e32 v178, v178
	v_rcp_f32_e32 v179, v179
	v_pk_mul_f32 v[172:173], v[118:119], v[172:173]
	v_pk_mul_f32 v[174:175], v[120:121], v[174:175]
	v_pk_mul_f32 v[176:177], v[114:115], v[176:177]
	v_pk_mul_f32 v[178:179], v[116:117], v[178:179]
	v_cvt_pk_bf16_f32 v140, v172, v173
	v_cvt_pk_bf16_f32 v141, v174, v175
	v_cvt_pk_bf16_f32 v142, v176, v177
	v_cvt_pk_bf16_f32 v143, v178, v179
	global_store_dwordx4 v138, v[140:143], s[6:7] nt
	v_pk_mul_f32 v[180:181], v[54:55], s[24:25] op_sel_hi:[1,0]
	v_pk_mul_f32 v[182:183], v[56:57], s[24:25] op_sel_hi:[1,0]
	v_pk_mul_f32 v[184:185], v[50:51], s[24:25] op_sel_hi:[1,0]
	v_pk_mul_f32 v[186:187], v[52:53], s[24:25] op_sel_hi:[1,0]
	v_exp_f32_e32 v180, v180
	v_exp_f32_e32 v181, v181
	v_exp_f32_e32 v182, v182
	v_exp_f32_e32 v183, v183
	v_exp_f32_e32 v184, v184
	v_exp_f32_e32 v185, v185
	v_exp_f32_e32 v186, v186
	v_exp_f32_e32 v187, v187
	v_pk_add_f32 v[180:181], v[180:181], 1.0 op_sel_hi:[1,0]
	v_pk_add_f32 v[182:183], v[182:183], 1.0 op_sel_hi:[1,0]
	v_pk_add_f32 v[184:185], v[184:185], 1.0 op_sel_hi:[1,0]
	v_pk_add_f32 v[186:187], v[186:187], 1.0 op_sel_hi:[1,0]
	v_rcp_f32_e32 v180, v180
	v_rcp_f32_e32 v181, v181
	v_rcp_f32_e32 v182, v182
	v_rcp_f32_e32 v183, v183
	v_rcp_f32_e32 v184, v184
	v_rcp_f32_e32 v185, v185
	v_rcp_f32_e32 v186, v186
	v_rcp_f32_e32 v187, v187
	v_pk_mul_f32 v[180:181], v[54:55], v[180:181]
	v_pk_mul_f32 v[182:183], v[56:57], v[182:183]
	v_pk_mul_f32 v[184:185], v[50:51], v[184:185]
	v_pk_mul_f32 v[186:187], v[52:53], v[186:187]
	v_cvt_pk_bf16_f32 v156, v180, v181
	v_cvt_pk_bf16_f32 v157, v182, v183
	v_cvt_pk_bf16_f32 v158, v184, v185
	v_cvt_pk_bf16_f32 v159, v186, v187
	global_store_dwordx4 v138, v[156:159], s[6:7] offset:256 nt
	s_add_u32 s6, s6, 0x8000
	s_addc_u32 s7, s7, 0
	v_pk_mul_f32 v[172:173], v[110:111], s[24:25] op_sel_hi:[1,0]
	v_pk_mul_f32 v[174:175], v[112:113], s[24:25] op_sel_hi:[1,0]
	v_pk_mul_f32 v[176:177], v[106:107], s[24:25] op_sel_hi:[1,0]
	v_pk_mul_f32 v[178:179], v[108:109], s[24:25] op_sel_hi:[1,0]
	v_exp_f32_e32 v172, v172
	v_exp_f32_e32 v173, v173
	v_exp_f32_e32 v174, v174
	v_exp_f32_e32 v175, v175
; __device__ __forceinline__ float sigm(float x) { return __builtin_amdgcn_rcpf(1.f + __expf(-x)); }
; __device__ __forceinline__ u32x4 pack8(const f32x4 v0, const f32x4 v1) { u32x4 w; w.x = cvt_pk_bf16(v0[0], v0[1]); w.y = cvt_pk_bf16(v0[2], v0[3]); w.z = cvt_pk_bf16(v1[0], v1[1]); w.w = cvt_pk_bf16(v1[2], v1[3]); return w; }
;     __device__ __forceinline__ void operator()(f32x4 (&acc)[2][2][4][2], const Unit& u, int wr, int wc, int fr, int fq) const {
;     ...
;             for (int ai = 0; ai < 2; ++ai)
; #pragma unroll
;                 for (int m = 0; m < 4; ++m) { bf16_t* rowp = base + (size_t)(ai * HALF + m * 16) * LDZ;
; #pragma unroll
;                     for (int bj = 0; bj < 2; ++bj) { f32x4 v0 = acc[ai][bj][m][0], v1 = acc[ai][bj][m][1];
;                         if (kind == 1) {
; #pragma unroll
;                             for (int e = 0; e < 4; ++e) { v0[e] = v0[e] * sigm(v0[e]); v1[e] = v1[e] * sigm(v1[e]); } }
;                         else if (kind == 2) { v0 = v0 * (0.125f * LOG2E); v1 = v1 * (0.125f * LOG2E); }
;                         else if (kind == 3) {
; #pragma unroll
;                             for (int e = 0; e < 4; ++e) { v0[e] = sigm(v0[e] + bv[bj][0][e]); v1[e] = sigm(v1[e] + bv[bj][1][e]); } }
;                         __builtin_nontemporal_store(pack8(v0, v1), (u32x4*)(rowp + bj * HALF)); } }
	v_exp_f32_e32 v176, v176
	v_exp_f32_e32 v177, v177
	v_exp_f32_e32 v178, v178
	v_exp_f32_e32 v179, v179
	v_pk_add_f32 v[172:173], v[172:173], 1.0 op_sel_hi:[1,0]
	v_pk_add_f32 v[174:175], v[174:175], 1.0 op_sel_hi:[1,0]
	v_pk_add_f32 v[176:177], v[176:177], 1.0 op_sel_hi:[1,0]
	v_pk_add_f32 v[178:179], v[178:179], 1.0 op_sel_hi:[1,0]
	v_rcp_f32_e32 v172, v172
	v_rcp_f32_e32 v173, v173
	v_rcp_f32_e32 v174, v174
	v_rcp_f32_e32 v175, v175
	v_rcp_f32_e32 v176, v176
	v_rcp_f32_e32 v177, v177
	v_rcp_f32_e32 v178, v178
	v_rcp_f32_e32 v179, v179
	v_pk_mul_f32 v[172:173], v[110:111], v[172:173]
	v_pk_mul_f32 v[174:175], v[112:113], v[174:175]
	v_pk_mul_f32 v[176:177], v[106:107], v[176:177]
	v_pk_mul_f32 v[178:179], v[108:109], v[178:179]
	v_cvt_pk_bf16_f32 v130, v172, v173
	v_cvt_pk_bf16_f32 v131, v174, v175
	v_cvt_pk_bf16_f32 v132, v176, v177
	v_cvt_pk_bf16_f32 v133, v178, v179
	global_store_dwordx4 v138, v[130:133], s[6:7] nt
	v_pk_mul_f32 v[180:181], v[46:47], s[24:25] op_sel_hi:[1,0]
	v_pk_mul_f32 v[182:183], v[48:49], s[24:25] op_sel_hi:[1,0]
	v_pk_mul_f32 v[184:185], v[42:43], s[24:25] op_sel_hi:[1,0]
	v_pk_mul_f32 v[186:187], v[44:45], s[24:25] op_sel_hi:[1,0]
	v_exp_f32_e32 v180, v180
	v_exp_f32_e32 v181, v181
	v_exp_f32_e32 v182, v182
	v_exp_f32_e32 v183, v183
	v_exp_f32_e32 v184, v184
	v_exp_f32_e32 v185, v185
	v_exp_f32_e32 v186, v186
	v_exp_f32_e32 v187, v187
	v_pk_add_f32 v[180:181], v[180:181], 1.0 op_sel_hi:[1,0]
	v_pk_add_f32 v[182:183], v[182:183], 1.0 op_sel_hi:[1,0]
	v_pk_add_f32 v[184:185], v[184:185], 1.0 op_sel_hi:[1,0]
	v_pk_add_f32 v[186:187], v[186:187], 1.0 op_sel_hi:[1,0]
	v_rcp_f32_e32 v180, v180
	v_rcp_f32_e32 v181, v181
	v_rcp_f32_e32 v182, v182
	v_rcp_f32_e32 v183, v183
	v_rcp_f32_e32 v184, v184
	v_rcp_f32_e32 v185, v185
	v_rcp_f32_e32 v186, v186
	v_rcp_f32_e32 v187, v187
	v_pk_mul_f32 v[180:181], v[46:47], v[180:181]
	v_pk_mul_f32 v[182:183], v[48:49], v[182:183]
	v_pk_mul_f32 v[184:185], v[42:43], v[184:185]
	v_pk_mul_f32 v[186:187], v[44:45], v[186:187]
	v_cvt_pk_bf16_f32 v134, v180, v181
	v_cvt_pk_bf16_f32 v135, v182, v183
	v_cvt_pk_bf16_f32 v136, v184, v185
	v_cvt_pk_bf16_f32 v137, v186, v187
	global_store_dwordx4 v138, v[134:137], s[6:7] offset:256 nt
	s_add_u32 s6, s6, 0x8000
	s_addc_u32 s7, s7, 0
	v_pk_mul_f32 v[172:173], v[102:103], s[24:25] op_sel_hi:[1,0]
	v_pk_mul_f32 v[174:175], v[104:105], s[24:25] op_sel_hi:[1,0]
	v_pk_mul_f32 v[176:177], v[98:99], s[24:25] op_sel_hi:[1,0]
	v_pk_mul_f32 v[178:179], v[100:101], s[24:25] op_sel_hi:[1,0]
	v_exp_f32_e32 v172, v172
	v_exp_f32_e32 v173, v173
	v_exp_f32_e32 v174, v174
	v_exp_f32_e32 v175, v175
	v_exp_f32_e32 v176, v176
	v_exp_f32_e32 v177, v177
	v_exp_f32_e32 v178, v178
	v_exp_f32_e32 v179, v179
	v_pk_add_f32 v[172:173], v[172:173], 1.0 op_sel_hi:[1,0]
	v_pk_add_f32 v[174:175], v[174:175], 1.0 op_sel_hi:[1,0]
	v_pk_add_f32 v[176:177], v[176:177], 1.0 op_sel_hi:[1,0]
	v_pk_add_f32 v[178:179], v[178:179], 1.0 op_sel_hi:[1,0]
	v_rcp_f32_e32 v172, v172
	v_rcp_f32_e32 v173, v173
	v_rcp_f32_e32 v174, v174
	v_rcp_f32_e32 v175, v175
	v_rcp_f32_e32 v176, v176
	v_rcp_f32_e32 v177, v177
	v_rcp_f32_e32 v178, v178
	v_rcp_f32_e32 v179, v179
	v_pk_mul_f32 v[172:173], v[102:103], v[172:173]
	v_pk_mul_f32 v[174:175], v[104:105], v[174:175]
	v_pk_mul_f32 v[176:177], v[98:99], v[176:177]
	v_pk_mul_f32 v[178:179], v[100:101], v[178:179]
	v_cvt_pk_bf16_f32 v140, v172, v173
	v_cvt_pk_bf16_f32 v141, v174, v175
	v_cvt_pk_bf16_f32 v142, v176, v177
	v_cvt_pk_bf16_f32 v143, v178, v179
	global_store_dwordx4 v138, v[140:143], s[6:7] nt
	v_pk_mul_f32 v[180:181], v[38:39], s[24:25] op_sel_hi:[1,0]
	v_pk_mul_f32 v[182:183], v[40:41], s[24:25] op_sel_hi:[1,0]
	v_pk_mul_f32 v[184:185], v[34:35], s[24:25] op_sel_hi:[1,0]
	v_pk_mul_f32 v[186:187], v[36:37], s[24:25] op_sel_hi:[1,0]
	v_exp_f32_e32 v180, v180
	v_exp_f32_e32 v181, v181
	v_exp_f32_e32 v182, v182
	v_exp_f32_e32 v183, v183
	v_exp_f32_e32 v184, v184
	v_exp_f32_e32 v185, v185
	v_exp_f32_e32 v186, v186
	v_exp_f32_e32 v187, v187
	v_pk_add_f32 v[180:181], v[180:181], 1.0 op_sel_hi:[1,0]
	v_pk_add_f32 v[182:183], v[182:183], 1.0 op_sel_hi:[1,0]
	v_pk_add_f32 v[184:185], v[184:185], 1.0 op_sel_hi:[1,0]
	v_pk_add_f32 v[186:187], v[186:187], 1.0 op_sel_hi:[1,0]
	v_rcp_f32_e32 v180, v180
	v_rcp_f32_e32 v181, v181
	v_rcp_f32_e32 v182, v182
	v_rcp_f32_e32 v183, v183
	v_rcp_f32_e32 v184, v184
	v_rcp_f32_e32 v185, v185
	v_rcp_f32_e32 v186, v186
	v_rcp_f32_e32 v187, v187
	v_pk_mul_f32 v[180:181], v[38:39], v[180:181]
	v_pk_mul_f32 v[182:183], v[40:41], v[182:183]
	v_pk_mul_f32 v[184:185], v[34:35], v[184:185]
	v_pk_mul_f32 v[186:187], v[36:37], v[186:187]
	v_cvt_pk_bf16_f32 v156, v180, v181
	v_cvt_pk_bf16_f32 v157, v182, v183
	v_cvt_pk_bf16_f32 v158, v184, v185
	v_cvt_pk_bf16_f32 v159, v186, v187
	global_store_dwordx4 v138, v[156:159], s[6:7] offset:256 nt
	s_add_u32 s6, s6, 0x28000
	s_addc_u32 s7, s7, 0
	v_pk_mul_f32 v[172:173], v[94:95], s[24:25] op_sel_hi:[1,0]
	v_pk_mul_f32 v[174:175], v[96:97], s[24:25] op_sel_hi:[1,0]
	v_pk_mul_f32 v[176:177], v[90:91], s[24:25] op_sel_hi:[1,0]
	v_pk_mul_f32 v[178:179], v[92:93], s[24:25] op_sel_hi:[1,0]
	v_exp_f32_e32 v172, v172
	v_exp_f32_e32 v173, v173
	v_exp_f32_e32 v174, v174
	v_exp_f32_e32 v175, v175
	v_exp_f32_e32 v176, v176
	v_exp_f32_e32 v177, v177
	v_exp_f32_e32 v178, v178
	v_exp_f32_e32 v179, v179
	v_pk_add_f32 v[172:173], v[172:173], 1.0 op_sel_hi:[1,0]
	v_pk_add_f32 v[174:175], v[174:175], 1.0 op_sel_hi:[1,0]
	v_pk_add_f32 v[176:177], v[176:177], 1.0 op_sel_hi:[1,0]
	v_pk_add_f32 v[178:179], v[178:179], 1.0 op_sel_hi:[1,0]
	v_rcp_f32_e32 v172, v172
	v_rcp_f32_e32 v173, v173
	v_rcp_f32_e32 v174, v174
; __device__ __forceinline__ float sigm(float x) { return __builtin_amdgcn_rcpf(1.f + __expf(-x)); }
; __device__ __forceinline__ u32x4 pack8(const f32x4 v0, const f32x4 v1) { u32x4 w; w.x = cvt_pk_bf16(v0[0], v0[1]); w.y = cvt_pk_bf16(v0[2], v0[3]); w.z = cvt_pk_bf16(v1[0], v1[1]); w.w = cvt_pk_bf16(v1[2], v1[3]); return w; }
;     __device__ __forceinline__ void operator()(f32x4 (&acc)[2][2][4][2], const Unit& u, int wr, int wc, int fr, int fq) const {
;     ...
;             for (int ai = 0; ai < 2; ++ai)
; #pragma unroll
;                 for (int m = 0; m < 4; ++m) { bf16_t* rowp = base + (size_t)(ai * HALF + m * 16) * LDZ;
; #pragma unroll
;                     for (int bj = 0; bj < 2; ++bj) { f32x4 v0 = acc[ai][bj][m][0], v1 = acc[ai][bj][m][1];
;                         if (kind == 1) {
; #pragma unroll
;                             for (int e = 0; e < 4; ++e) { v0[e] = v0[e] * sigm(v0[e]); v1[e] = v1[e] * sigm(v1[e]); } }
;                         else if (kind == 2) { v0 = v0 * (0.125f * LOG2E); v1 = v1 * (0.125f * LOG2E); }
;                         else if (kind == 3) {
; #pragma unroll
;                             for (int e = 0; e < 4; ++e) { v0[e] = sigm(v0[e] + bv[bj][0][e]); v1[e] = sigm(v1[e] + bv[bj][1][e]); } }
;                         __builtin_nontemporal_store(pack8(v0, v1), (u32x4*)(rowp + bj * HALF)); } }
	v_rcp_f32_e32 v175, v175
	v_rcp_f32_e32 v176, v176
	v_rcp_f32_e32 v177, v177
	v_rcp_f32_e32 v178, v178
	v_rcp_f32_e32 v179, v179
	v_pk_mul_f32 v[172:173], v[94:95], v[172:173]
	v_pk_mul_f32 v[174:175], v[96:97], v[174:175]
	v_pk_mul_f32 v[176:177], v[90:91], v[176:177]
	v_pk_mul_f32 v[178:179], v[92:93], v[178:179]
	v_cvt_pk_bf16_f32 v130, v172, v173
	v_cvt_pk_bf16_f32 v131, v174, v175
	v_cvt_pk_bf16_f32 v132, v176, v177
	v_cvt_pk_bf16_f32 v133, v178, v179
	global_store_dwordx4 v138, v[130:133], s[6:7] nt
	v_pk_mul_f32 v[180:181], v[30:31], s[24:25] op_sel_hi:[1,0]
	v_pk_mul_f32 v[182:183], v[32:33], s[24:25] op_sel_hi:[1,0]
	v_pk_mul_f32 v[184:185], v[26:27], s[24:25] op_sel_hi:[1,0]
	v_pk_mul_f32 v[186:187], v[28:29], s[24:25] op_sel_hi:[1,0]
	v_exp_f32_e32 v180, v180
	v_exp_f32_e32 v181, v181
	v_exp_f32_e32 v182, v182
	v_exp_f32_e32 v183, v183
	v_exp_f32_e32 v184, v184
	v_exp_f32_e32 v185, v185
	v_exp_f32_e32 v186, v186
	v_exp_f32_e32 v187, v187
	v_pk_add_f32 v[180:181], v[180:181], 1.0 op_sel_hi:[1,0]
	v_pk_add_f32 v[182:183], v[182:183], 1.0 op_sel_hi:[1,0]
	v_pk_add_f32 v[184:185], v[184:185], 1.0 op_sel_hi:[1,0]
	v_pk_add_f32 v[186:187], v[186:187], 1.0 op_sel_hi:[1,0]
	v_rcp_f32_e32 v180, v180
	v_rcp_f32_e32 v181, v181
	v_rcp_f32_e32 v182, v182
	v_rcp_f32_e32 v183, v183
	v_rcp_f32_e32 v184, v184
	v_rcp_f32_e32 v185, v185
	v_rcp_f32_e32 v186, v186
	v_rcp_f32_e32 v187, v187
	v_pk_mul_f32 v[180:181], v[30:31], v[180:181]
	v_pk_mul_f32 v[182:183], v[32:33], v[182:183]
	v_pk_mul_f32 v[184:185], v[26:27], v[184:185]
	v_pk_mul_f32 v[186:187], v[28:29], v[186:187]
	v_cvt_pk_bf16_f32 v134, v180, v181
	v_cvt_pk_bf16_f32 v135, v182, v183
	v_cvt_pk_bf16_f32 v136, v184, v185
	v_cvt_pk_bf16_f32 v137, v186, v187
	global_store_dwordx4 v138, v[134:137], s[6:7] offset:256 nt
	s_add_u32 s6, s6, 0x8000
	s_addc_u32 s7, s7, 0
	v_pk_mul_f32 v[172:173], v[86:87], s[24:25] op_sel_hi:[1,0]
	v_pk_mul_f32 v[174:175], v[88:89], s[24:25] op_sel_hi:[1,0]
	v_pk_mul_f32 v[176:177], v[82:83], s[24:25] op_sel_hi:[1,0]
	v_pk_mul_f32 v[178:179], v[84:85], s[24:25] op_sel_hi:[1,0]
	v_exp_f32_e32 v172, v172
	v_exp_f32_e32 v173, v173
	v_exp_f32_e32 v174, v174
	v_exp_f32_e32 v175, v175
	v_exp_f32_e32 v176, v176
	v_exp_f32_e32 v177, v177
	v_exp_f32_e32 v178, v178
	v_exp_f32_e32 v179, v179
	v_pk_add_f32 v[172:173], v[172:173], 1.0 op_sel_hi:[1,0]
	v_pk_add_f32 v[174:175], v[174:175], 1.0 op_sel_hi:[1,0]
	v_pk_add_f32 v[176:177], v[176:177], 1.0 op_sel_hi:[1,0]
	v_pk_add_f32 v[178:179], v[178:179], 1.0 op_sel_hi:[1,0]
	v_rcp_f32_e32 v172, v172
	v_rcp_f32_e32 v173, v173
	v_rcp_f32_e32 v174, v174
	v_rcp_f32_e32 v175, v175
	v_rcp_f32_e32 v176, v176
	v_rcp_f32_e32 v177, v177
	v_rcp_f32_e32 v178, v178
	v_rcp_f32_e32 v179, v179
	v_pk_mul_f32 v[172:173], v[86:87], v[172:173]
	v_pk_mul_f32 v[174:175], v[88:89], v[174:175]
	v_pk_mul_f32 v[176:177], v[82:83], v[176:177]
	v_pk_mul_f32 v[178:179], v[84:85], v[178:179]
	v_cvt_pk_bf16_f32 v140, v172, v173
	v_cvt_pk_bf16_f32 v141, v174, v175
	v_cvt_pk_bf16_f32 v142, v176, v177
	v_cvt_pk_bf16_f32 v143, v178, v179
	global_store_dwordx4 v138, v[140:143], s[6:7] nt
	v_pk_mul_f32 v[180:181], v[22:23], s[24:25] op_sel_hi:[1,0]
	v_pk_mul_f32 v[182:183], v[24:25], s[24:25] op_sel_hi:[1,0]
	v_pk_mul_f32 v[184:185], v[18:19], s[24:25] op_sel_hi:[1,0]
	v_pk_mul_f32 v[186:187], v[20:21], s[24:25] op_sel_hi:[1,0]
	v_exp_f32_e32 v180, v180
	v_exp_f32_e32 v181, v181
	v_exp_f32_e32 v182, v182
	v_exp_f32_e32 v183, v183
	v_exp_f32_e32 v184, v184
	v_exp_f32_e32 v185, v185
	v_exp_f32_e32 v186, v186
	v_exp_f32_e32 v187, v187
	v_pk_add_f32 v[180:181], v[180:181], 1.0 op_sel_hi:[1,0]
	v_pk_add_f32 v[182:183], v[182:183], 1.0 op_sel_hi:[1,0]
	v_pk_add_f32 v[184:185], v[184:185], 1.0 op_sel_hi:[1,0]
	v_pk_add_f32 v[186:187], v[186:187], 1.0 op_sel_hi:[1,0]
	v_rcp_f32_e32 v180, v180
	v_rcp_f32_e32 v181, v181
	v_rcp_f32_e32 v182, v182
	v_rcp_f32_e32 v183, v183
	v_rcp_f32_e32 v184, v184
	v_rcp_f32_e32 v185, v185
	v_rcp_f32_e32 v186, v186
	v_rcp_f32_e32 v187, v187
	v_pk_mul_f32 v[180:181], v[22:23], v[180:181]
	v_pk_mul_f32 v[182:183], v[24:25], v[182:183]
	v_pk_mul_f32 v[184:185], v[18:19], v[184:185]
	v_pk_mul_f32 v[186:187], v[20:21], v[186:187]
	v_cvt_pk_bf16_f32 v156, v180, v181
	v_cvt_pk_bf16_f32 v157, v182, v183
	v_cvt_pk_bf16_f32 v158, v184, v185
	v_cvt_pk_bf16_f32 v159, v186, v187
	global_store_dwordx4 v138, v[156:159], s[6:7] offset:256 nt
	s_add_u32 s6, s6, 0x8000
	s_addc_u32 s7, s7, 0
	v_pk_mul_f32 v[172:173], v[78:79], s[24:25] op_sel_hi:[1,0]
	v_pk_mul_f32 v[174:175], v[80:81], s[24:25] op_sel_hi:[1,0]
	v_pk_mul_f32 v[176:177], v[74:75], s[24:25] op_sel_hi:[1,0]
	v_pk_mul_f32 v[178:179], v[76:77], s[24:25] op_sel_hi:[1,0]
	v_exp_f32_e32 v172, v172
	v_exp_f32_e32 v173, v173
	v_exp_f32_e32 v174, v174
	v_exp_f32_e32 v175, v175
	v_exp_f32_e32 v176, v176
	v_exp_f32_e32 v177, v177
	v_exp_f32_e32 v178, v178
	v_exp_f32_e32 v179, v179
	v_pk_add_f32 v[172:173], v[172:173], 1.0 op_sel_hi:[1,0]
	v_pk_add_f32 v[174:175], v[174:175], 1.0 op_sel_hi:[1,0]
	v_pk_add_f32 v[176:177], v[176:177], 1.0 op_sel_hi:[1,0]
	v_pk_add_f32 v[178:179], v[178:179], 1.0 op_sel_hi:[1,0]
	v_rcp_f32_e32 v172, v172
	v_rcp_f32_e32 v173, v173
	v_rcp_f32_e32 v174, v174
	v_rcp_f32_e32 v175, v175
	v_rcp_f32_e32 v176, v176
	v_rcp_f32_e32 v177, v177
	v_rcp_f32_e32 v178, v178
	v_rcp_f32_e32 v179, v179
	v_pk_mul_f32 v[172:173], v[78:79], v[172:173]
	v_pk_mul_f32 v[174:175], v[80:81], v[174:175]
	v_pk_mul_f32 v[176:177], v[74:75], v[176:177]
	v_pk_mul_f32 v[178:179], v[76:77], v[178:179]
	v_cvt_pk_bf16_f32 v130, v172, v173
	v_cvt_pk_bf16_f32 v131, v174, v175
	v_cvt_pk_bf16_f32 v132, v176, v177
; __device__ __forceinline__ float sigm(float x) { return __builtin_amdgcn_rcpf(1.f + __expf(-x)); }
; __device__ __forceinline__ u32x4 pack8(const f32x4 v0, const f32x4 v1) { u32x4 w; w.x = cvt_pk_bf16(v0[0], v0[1]); w.y = cvt_pk_bf16(v0[2], v0[3]); w.z = cvt_pk_bf16(v1[0], v1[1]); w.w = cvt_pk_bf16(v1[2], v1[3]); return w; }
;     __device__ __forceinline__ void operator()(f32x4 (&acc)[2][2][4][2], const Unit& u, int wr, int wc, int fr, int fq) const {
;     ...
;             for (int ai = 0; ai < 2; ++ai)
; #pragma unroll
;                 for (int m = 0; m < 4; ++m) { bf16_t* rowp = base + (size_t)(ai * HALF + m * 16) * LDZ;
; #pragma unroll
;                     for (int bj = 0; bj < 2; ++bj) { f32x4 v0 = acc[ai][bj][m][0], v1 = acc[ai][bj][m][1];
;                         if (kind == 1) {
; #pragma unroll
;                             for (int e = 0; e < 4; ++e) { v0[e] = v0[e] * sigm(v0[e]); v1[e] = v1[e] * sigm(v1[e]); } }
;                         else if (kind == 2) { v0 = v0 * (0.125f * LOG2E); v1 = v1 * (0.125f * LOG2E); }
;                         else if (kind == 3) {
; #pragma unroll
;                             for (int e = 0; e < 4; ++e) { v0[e] = sigm(v0[e] + bv[bj][0][e]); v1[e] = sigm(v1[e] + bv[bj][1][e]); } }
;                         __builtin_nontemporal_store(pack8(v0, v1), (u32x4*)(rowp + bj * HALF)); } }
	v_cvt_pk_bf16_f32 v133, v178, v179
	global_store_dwordx4 v138, v[130:133], s[6:7] nt
	v_pk_mul_f32 v[180:181], v[14:15], s[24:25] op_sel_hi:[1,0]
	v_pk_mul_f32 v[182:183], v[16:17], s[24:25] op_sel_hi:[1,0]
	v_pk_mul_f32 v[184:185], v[10:11], s[24:25] op_sel_hi:[1,0]
	v_pk_mul_f32 v[186:187], v[12:13], s[24:25] op_sel_hi:[1,0]
	v_exp_f32_e32 v180, v180
	v_exp_f32_e32 v181, v181
	v_exp_f32_e32 v182, v182
	v_exp_f32_e32 v183, v183
	v_exp_f32_e32 v184, v184
	v_exp_f32_e32 v185, v185
	v_exp_f32_e32 v186, v186
	v_exp_f32_e32 v187, v187
	v_pk_add_f32 v[180:181], v[180:181], 1.0 op_sel_hi:[1,0]
	v_pk_add_f32 v[182:183], v[182:183], 1.0 op_sel_hi:[1,0]
	v_pk_add_f32 v[184:185], v[184:185], 1.0 op_sel_hi:[1,0]
	v_pk_add_f32 v[186:187], v[186:187], 1.0 op_sel_hi:[1,0]
	v_rcp_f32_e32 v180, v180
	v_rcp_f32_e32 v181, v181
	v_rcp_f32_e32 v182, v182
	v_rcp_f32_e32 v183, v183
	v_rcp_f32_e32 v184, v184
	v_rcp_f32_e32 v185, v185
	v_rcp_f32_e32 v186, v186
	v_rcp_f32_e32 v187, v187
	v_pk_mul_f32 v[180:181], v[14:15], v[180:181]
	v_pk_mul_f32 v[182:183], v[16:17], v[182:183]
	v_pk_mul_f32 v[184:185], v[10:11], v[184:185]
	v_pk_mul_f32 v[186:187], v[12:13], v[186:187]
	v_cvt_pk_bf16_f32 v134, v180, v181
	v_cvt_pk_bf16_f32 v135, v182, v183
	v_cvt_pk_bf16_f32 v136, v184, v185
	v_cvt_pk_bf16_f32 v137, v186, v187
	global_store_dwordx4 v138, v[134:137], s[6:7] offset:256 nt
	s_add_u32 s6, s6, 0x8000
	s_addc_u32 s7, s7, 0
	v_pk_mul_f32 v[172:173], v[70:71], s[24:25] op_sel_hi:[1,0]
	v_pk_mul_f32 v[174:175], v[72:73], s[24:25] op_sel_hi:[1,0]
	v_pk_mul_f32 v[176:177], v[66:67], s[24:25] op_sel_hi:[1,0]
	v_pk_mul_f32 v[178:179], v[68:69], s[24:25] op_sel_hi:[1,0]
	v_exp_f32_e32 v172, v172
	v_exp_f32_e32 v173, v173
	v_exp_f32_e32 v174, v174
	v_exp_f32_e32 v175, v175
	v_exp_f32_e32 v176, v176
	v_exp_f32_e32 v177, v177
	v_exp_f32_e32 v178, v178
	v_exp_f32_e32 v179, v179
	v_pk_add_f32 v[172:173], v[172:173], 1.0 op_sel_hi:[1,0]
	v_pk_add_f32 v[174:175], v[174:175], 1.0 op_sel_hi:[1,0]
	v_pk_add_f32 v[176:177], v[176:177], 1.0 op_sel_hi:[1,0]
	v_pk_add_f32 v[178:179], v[178:179], 1.0 op_sel_hi:[1,0]
	v_rcp_f32_e32 v172, v172
	v_rcp_f32_e32 v173, v173
	v_rcp_f32_e32 v174, v174
	v_rcp_f32_e32 v175, v175
	v_rcp_f32_e32 v176, v176
	v_rcp_f32_e32 v177, v177
	v_rcp_f32_e32 v178, v178
	v_rcp_f32_e32 v179, v179
	v_pk_mul_f32 v[172:173], v[70:71], v[172:173]
	v_pk_mul_f32 v[174:175], v[72:73], v[174:175]
	v_pk_mul_f32 v[176:177], v[66:67], v[176:177]
	v_pk_mul_f32 v[178:179], v[68:69], v[178:179]
	v_cvt_pk_bf16_f32 v140, v172, v173
	v_cvt_pk_bf16_f32 v141, v174, v175
	v_cvt_pk_bf16_f32 v142, v176, v177
	v_cvt_pk_bf16_f32 v143, v178, v179
	global_store_dwordx4 v138, v[140:143], s[6:7] nt
	v_pk_mul_f32 v[180:181], v[6:7], s[24:25] op_sel_hi:[1,0]
	v_pk_mul_f32 v[182:183], v[8:9], s[24:25] op_sel_hi:[1,0]
	v_pk_mul_f32 v[184:185], v[2:3], s[24:25] op_sel_hi:[1,0]
	v_pk_mul_f32 v[186:187], v[4:5], s[24:25] op_sel_hi:[1,0]
	v_exp_f32_e32 v180, v180
	v_exp_f32_e32 v181, v181
	v_exp_f32_e32 v182, v182
	v_exp_f32_e32 v183, v183
	v_exp_f32_e32 v184, v184
	v_exp_f32_e32 v185, v185
	v_exp_f32_e32 v186, v186
	v_exp_f32_e32 v187, v187
	v_pk_add_f32 v[180:181], v[180:181], 1.0 op_sel_hi:[1,0]
	v_pk_add_f32 v[182:183], v[182:183], 1.0 op_sel_hi:[1,0]
	v_pk_add_f32 v[184:185], v[184:185], 1.0 op_sel_hi:[1,0]
	v_pk_add_f32 v[186:187], v[186:187], 1.0 op_sel_hi:[1,0]
	v_rcp_f32_e32 v180, v180
	v_rcp_f32_e32 v181, v181
	v_rcp_f32_e32 v182, v182
	v_rcp_f32_e32 v183, v183
	v_rcp_f32_e32 v184, v184
	v_rcp_f32_e32 v185, v185
	v_rcp_f32_e32 v186, v186
	v_rcp_f32_e32 v187, v187
	v_pk_mul_f32 v[180:181], v[6:7], v[180:181]
	v_pk_mul_f32 v[182:183], v[8:9], v[182:183]
	v_pk_mul_f32 v[184:185], v[2:3], v[184:185]
	v_pk_mul_f32 v[186:187], v[4:5], v[186:187]
	v_cvt_pk_bf16_f32 v156, v180, v181
	v_cvt_pk_bf16_f32 v157, v182, v183
	v_cvt_pk_bf16_f32 v158, v184, v185
	v_cvt_pk_bf16_f32 v159, v186, v187
	global_store_dwordx4 v138, v[156:159], s[6:7] offset:256 nt
	s_branch .Lepi1_done
.Lepi1_k2:
	s_mov_b64 s[6:7], s[50:51]
	v_pk_mul_f32 v[172:173], v[126:127], s[26:27] op_sel_hi:[1,0]
	v_pk_mul_f32 v[174:175], v[128:129], s[26:27] op_sel_hi:[1,0]
	v_pk_mul_f32 v[176:177], v[122:123], s[26:27] op_sel_hi:[1,0]
	v_pk_mul_f32 v[178:179], v[124:125], s[26:27] op_sel_hi:[1,0]
	v_cvt_pk_bf16_f32 v130, v172, v173
	v_cvt_pk_bf16_f32 v131, v174, v175
	v_cvt_pk_bf16_f32 v132, v176, v177
	v_cvt_pk_bf16_f32 v133, v178, v179
	global_store_dwordx4 v138, v[130:133], s[6:7] nt
	v_pk_mul_f32 v[180:181], v[62:63], s[26:27] op_sel_hi:[1,0]
	v_pk_mul_f32 v[182:183], v[64:65], s[26:27] op_sel_hi:[1,0]
	v_pk_mul_f32 v[184:185], v[58:59], s[26:27] op_sel_hi:[1,0]
	v_pk_mul_f32 v[186:187], v[60:61], s[26:27] op_sel_hi:[1,0]
	v_cvt_pk_bf16_f32 v134, v180, v181
	v_cvt_pk_bf16_f32 v135, v182, v183
	v_cvt_pk_bf16_f32 v136, v184, v185
	v_cvt_pk_bf16_f32 v137, v186, v187
	global_store_dwordx4 v138, v[134:137], s[6:7] offset:256 nt
	s_add_u32 s6, s6, 0x8000
	s_addc_u32 s7, s7, 0
	v_pk_mul_f32 v[172:173], v[118:119], s[26:27] op_sel_hi:[1,0]
	v_pk_mul_f32 v[174:175], v[120:121], s[26:27] op_sel_hi:[1,0]
	v_pk_mul_f32 v[176:177], v[114:115], s[26:27] op_sel_hi:[1,0]
	v_pk_mul_f32 v[178:179], v[116:117], s[26:27] op_sel_hi:[1,0]
	v_cvt_pk_bf16_f32 v140, v172, v173
	v_cvt_pk_bf16_f32 v141, v174, v175
	v_cvt_pk_bf16_f32 v142, v176, v177
	v_cvt_pk_bf16_f32 v143, v178, v179
	global_store_dwordx4 v138, v[140:143], s[6:7] nt
	v_pk_mul_f32 v[180:181], v[54:55], s[26:27] op_sel_hi:[1,0]
	v_pk_mul_f32 v[182:183], v[56:57], s[26:27] op_sel_hi:[1,0]
	v_pk_mul_f32 v[184:185], v[50:51], s[26:27] op_sel_hi:[1,0]
	v_pk_mul_f32 v[186:187], v[52:53], s[26:27] op_sel_hi:[1,0]
; __device__ __forceinline__ float sigm(float x) { return __builtin_amdgcn_rcpf(1.f + __expf(-x)); }
; __device__ __forceinline__ u32x4 pack8(const f32x4 v0, const f32x4 v1) { u32x4 w; w.x = cvt_pk_bf16(v0[0], v0[1]); w.y = cvt_pk_bf16(v0[2], v0[3]); w.z = cvt_pk_bf16(v1[0], v1[1]); w.w = cvt_pk_bf16(v1[2], v1[3]); return w; }
;     __device__ __forceinline__ void operator()(f32x4 (&acc)[2][2][4][2], const Unit& u, int wr, int wc, int fr, int fq) const {
;     ...
;             for (int ai = 0; ai < 2; ++ai)
; #pragma unroll
;                 for (int m = 0; m < 4; ++m) { bf16_t* rowp = base + (size_t)(ai * HALF + m * 16) * LDZ;
; #pragma unroll
;                     for (int bj = 0; bj < 2; ++bj) { f32x4 v0 = acc[ai][bj][m][0], v1 = acc[ai][bj][m][1];
;                         if (kind == 1) {
; #pragma unroll
;                             for (int e = 0; e < 4; ++e) { v0[e] = v0[e] * sigm(v0[e]); v1[e] = v1[e] * sigm(v1[e]); } }
;                         else if (kind == 2) { v0 = v0 * (0.125f * LOG2E); v1 = v1 * (0.125f * LOG2E); }
;                         else if (kind == 3) {
; #pragma unroll
;                             for (int e = 0; e < 4; ++e) { v0[e] = sigm(v0[e] + bv[bj][0][e]); v1[e] = sigm(v1[e] + bv[bj][1][e]); } }
;                         __builtin_nontemporal_store(pack8(v0, v1), (u32x4*)(rowp + bj * HALF)); } }
	v_cvt_pk_bf16_f32 v156, v180, v181
	v_cvt_pk_bf16_f32 v157, v182, v183
	v_cvt_pk_bf16_f32 v158, v184, v185
	v_cvt_pk_bf16_f32 v159, v186, v187
	global_store_dwordx4 v138, v[156:159], s[6:7] offset:256 nt
	s_add_u32 s6, s6, 0x8000
	s_addc_u32 s7, s7, 0
	v_pk_mul_f32 v[172:173], v[110:111], s[26:27] op_sel_hi:[1,0]
	v_pk_mul_f32 v[174:175], v[112:113], s[26:27] op_sel_hi:[1,0]
	v_pk_mul_f32 v[176:177], v[106:107], s[26:27] op_sel_hi:[1,0]
	v_pk_mul_f32 v[178:179], v[108:109], s[26:27] op_sel_hi:[1,0]
	v_cvt_pk_bf16_f32 v130, v172, v173
	v_cvt_pk_bf16_f32 v131, v174, v175
	v_cvt_pk_bf16_f32 v132, v176, v177
	v_cvt_pk_bf16_f32 v133, v178, v179
	global_store_dwordx4 v138, v[130:133], s[6:7] nt
	v_pk_mul_f32 v[180:181], v[46:47], s[26:27] op_sel_hi:[1,0]
	v_pk_mul_f32 v[182:183], v[48:49], s[26:27] op_sel_hi:[1,0]
	v_pk_mul_f32 v[184:185], v[42:43], s[26:27] op_sel_hi:[1,0]
	v_pk_mul_f32 v[186:187], v[44:45], s[26:27] op_sel_hi:[1,0]
	v_cvt_pk_bf16_f32 v134, v180, v181
	v_cvt_pk_bf16_f32 v135, v182, v183
	v_cvt_pk_bf16_f32 v136, v184, v185
	v_cvt_pk_bf16_f32 v137, v186, v187
	global_store_dwordx4 v138, v[134:137], s[6:7] offset:256 nt
	s_add_u32 s6, s6, 0x8000
	s_addc_u32 s7, s7, 0
	v_pk_mul_f32 v[172:173], v[102:103], s[26:27] op_sel_hi:[1,0]
	v_pk_mul_f32 v[174:175], v[104:105], s[26:27] op_sel_hi:[1,0]
	v_pk_mul_f32 v[176:177], v[98:99], s[26:27] op_sel_hi:[1,0]
	v_pk_mul_f32 v[178:179], v[100:101], s[26:27] op_sel_hi:[1,0]
	v_cvt_pk_bf16_f32 v140, v172, v173
	v_cvt_pk_bf16_f32 v141, v174, v175
	v_cvt_pk_bf16_f32 v142, v176, v177
	v_cvt_pk_bf16_f32 v143, v178, v179
	global_store_dwordx4 v138, v[140:143], s[6:7] nt
	v_pk_mul_f32 v[180:181], v[38:39], s[26:27] op_sel_hi:[1,0]
	v_pk_mul_f32 v[182:183], v[40:41], s[26:27] op_sel_hi:[1,0]
	v_pk_mul_f32 v[184:185], v[34:35], s[26:27] op_sel_hi:[1,0]
	v_pk_mul_f32 v[186:187], v[36:37], s[26:27] op_sel_hi:[1,0]
	v_cvt_pk_bf16_f32 v156, v180, v181
	v_cvt_pk_bf16_f32 v157, v182, v183
	v_cvt_pk_bf16_f32 v158, v184, v185
	v_cvt_pk_bf16_f32 v159, v186, v187
	global_store_dwordx4 v138, v[156:159], s[6:7] offset:256 nt
	s_add_u32 s6, s6, 0x28000
	s_addc_u32 s7, s7, 0
	v_pk_mul_f32 v[172:173], v[94:95], s[26:27] op_sel_hi:[1,0]
	v_pk_mul_f32 v[174:175], v[96:97], s[26:27] op_sel_hi:[1,0]
	v_pk_mul_f32 v[176:177], v[90:91], s[26:27] op_sel_hi:[1,0]
	v_pk_mul_f32 v[178:179], v[92:93], s[26:27] op_sel_hi:[1,0]
	v_cvt_pk_bf16_f32 v130, v172, v173
	v_cvt_pk_bf16_f32 v131, v174, v175
	v_cvt_pk_bf16_f32 v132, v176, v177
	v_cvt_pk_bf16_f32 v133, v178, v179
	global_store_dwordx4 v138, v[130:133], s[6:7] nt
	v_pk_mul_f32 v[180:181], v[30:31], s[26:27] op_sel_hi:[1,0]
	v_pk_mul_f32 v[182:183], v[32:33], s[26:27] op_sel_hi:[1,0]
	v_pk_mul_f32 v[184:185], v[26:27], s[26:27] op_sel_hi:[1,0]
	v_pk_mul_f32 v[186:187], v[28:29], s[26:27] op_sel_hi:[1,0]
	v_cvt_pk_bf16_f32 v134, v180, v181
	v_cvt_pk_bf16_f32 v135, v182, v183
	v_cvt_pk_bf16_f32 v136, v184, v185
	v_cvt_pk_bf16_f32 v137, v186, v187
	global_store_dwordx4 v138, v[134:137], s[6:7] offset:256 nt
	s_add_u32 s6, s6, 0x8000
	s_addc_u32 s7, s7, 0
	v_pk_mul_f32 v[172:173], v[86:87], s[26:27] op_sel_hi:[1,0]
	v_pk_mul_f32 v[174:175], v[88:89], s[26:27] op_sel_hi:[1,0]
	v_pk_mul_f32 v[176:177], v[82:83], s[26:27] op_sel_hi:[1,0]
	v_pk_mul_f32 v[178:179], v[84:85], s[26:27] op_sel_hi:[1,0]
	v_cvt_pk_bf16_f32 v140, v172, v173
	v_cvt_pk_bf16_f32 v141, v174, v175
	v_cvt_pk_bf16_f32 v142, v176, v177
	v_cvt_pk_bf16_f32 v143, v178, v179
	global_store_dwordx4 v138, v[140:143], s[6:7] nt
	v_pk_mul_f32 v[180:181], v[22:23], s[26:27] op_sel_hi:[1,0]
	v_pk_mul_f32 v[182:183], v[24:25], s[26:27] op_sel_hi:[1,0]
	v_pk_mul_f32 v[184:185], v[18:19], s[26:27] op_sel_hi:[1,0]
	v_pk_mul_f32 v[186:187], v[20:21], s[26:27] op_sel_hi:[1,0]
	v_cvt_pk_bf16_f32 v156, v180, v181
	v_cvt_pk_bf16_f32 v157, v182, v183
	v_cvt_pk_bf16_f32 v158, v184, v185
	v_cvt_pk_bf16_f32 v159, v186, v187
	global_store_dwordx4 v138, v[156:159], s[6:7] offset:256 nt
	s_add_u32 s6, s6, 0x8000
	s_addc_u32 s7, s7, 0
	v_pk_mul_f32 v[172:173], v[78:79], s[26:27] op_sel_hi:[1,0]
	v_pk_mul_f32 v[174:175], v[80:81], s[26:27] op_sel_hi:[1,0]
	v_pk_mul_f32 v[176:177], v[74:75], s[26:27] op_sel_hi:[1,0]
	v_pk_mul_f32 v[178:179], v[76:77], s[26:27] op_sel_hi:[1,0]
	v_cvt_pk_bf16_f32 v130, v172, v173
	v_cvt_pk_bf16_f32 v131, v174, v175
	v_cvt_pk_bf16_f32 v132, v176, v177
	v_cvt_pk_bf16_f32 v133, v178, v179
	global_store_dwordx4 v138, v[130:133], s[6:7] nt
	v_pk_mul_f32 v[180:181], v[14:15], s[26:27] op_sel_hi:[1,0]
	v_pk_mul_f32 v[182:183], v[16:17], s[26:27] op_sel_hi:[1,0]
	v_pk_mul_f32 v[184:185], v[10:11], s[26:27] op_sel_hi:[1,0]
	v_pk_mul_f32 v[186:187], v[12:13], s[26:27] op_sel_hi:[1,0]
	v_cvt_pk_bf16_f32 v134, v180, v181
	v_cvt_pk_bf16_f32 v135, v182, v183
	v_cvt_pk_bf16_f32 v136, v184, v185
	v_cvt_pk_bf16_f32 v137, v186, v187
	global_store_dwordx4 v138, v[134:137], s[6:7] offset:256 nt
	s_add_u32 s6, s6, 0x8000
	s_addc_u32 s7, s7, 0
	v_pk_mul_f32 v[172:173], v[70:71], s[26:27] op_sel_hi:[1,0]
	v_pk_mul_f32 v[174:175], v[72:73], s[26:27] op_sel_hi:[1,0]
	v_pk_mul_f32 v[176:177], v[66:67], s[26:27] op_sel_hi:[1,0]
	v_pk_mul_f32 v[178:179], v[68:69], s[26:27] op_sel_hi:[1,0]
	v_cvt_pk_bf16_f32 v140, v172, v173
	v_cvt_pk_bf16_f32 v141, v174, v175
	v_cvt_pk_bf16_f32 v142, v176, v177
	v_cvt_pk_bf16_f32 v143, v178, v179
	global_store_dwordx4 v138, v[140:143], s[6:7] nt
	v_pk_mul_f32 v[180:181], v[6:7], s[26:27] op_sel_hi:[1,0]
	v_pk_mul_f32 v[182:183], v[8:9], s[26:27] op_sel_hi:[1,0]
	v_pk_mul_f32 v[184:185], v[2:3], s[26:27] op_sel_hi:[1,0]
	v_pk_mul_f32 v[186:187], v[4:5], s[26:27] op_sel_hi:[1,0]
	v_cvt_pk_bf16_f32 v156, v180, v181
	v_cvt_pk_bf16_f32 v157, v182, v183
	v_cvt_pk_bf16_f32 v158, v184, v185
	v_cvt_pk_bf16_f32 v159, v186, v187
	global_store_dwordx4 v138, v[156:159], s[6:7] offset:256 nt
	s_branch .Lepi1_done
; __device__ __forceinline__ float sigm(float x) { return __builtin_amdgcn_rcpf(1.f + __expf(-x)); }
; __device__ __forceinline__ u32x4 pack8(const f32x4 v0, const f32x4 v1) { u32x4 w; w.x = cvt_pk_bf16(v0[0], v0[1]); w.y = cvt_pk_bf16(v0[2], v0[3]); w.z = cvt_pk_bf16(v1[0], v1[1]); w.w = cvt_pk_bf16(v1[2], v1[3]); return w; }
;     __device__ __forceinline__ void operator()(f32x4 (&acc)[2][2][4][2], const Unit& u, int wr, int wc, int fr, int fq) const {
;     ...
;             f32x4 bv[2][2];
; #pragma unroll
;             for (int bj = 0; bj < 2; ++bj)
; #pragma unroll
;                 for (int n = 0; n < 2; ++n) bv[bj][n] = (kind == 3) ? *(const f32x4*)(b_merge + (pn * 256 - 8192) + wc * 32 + 8 * fq + bj * HALF + 4 * n) : (f32x4){0.f, 0.f, 0.f, 0.f};
; #pragma unroll
;             for (int ai = 0; ai < 2; ++ai)
; #pragma unroll
;                 for (int m = 0; m < 4; ++m) { bf16_t* rowp = base + (size_t)(ai * HALF + m * 16) * LDZ;
; #pragma unroll
;                     for (int bj = 0; bj < 2; ++bj) { f32x4 v0 = acc[ai][bj][m][0], v1 = acc[ai][bj][m][1];
;                         if (kind == 1) {
; #pragma unroll
;                             for (int e = 0; e < 4; ++e) { v0[e] = v0[e] * sigm(v0[e]); v1[e] = v1[e] * sigm(v1[e]); } }
;                         else if (kind == 2) { v0 = v0 * (0.125f * LOG2E); v1 = v1 * (0.125f * LOG2E); }
;                         else if (kind == 3) {
; #pragma unroll
;                             for (int e = 0; e < 4; ++e) { v0[e] = sigm(v0[e] + bv[bj][0][e]); v1[e] = sigm(v1[e] + bv[bj][1][e]); } }
;                         __builtin_nontemporal_store(pack8(v0, v1), (u32x4*)(rowp + bj * HALF)); } }
.Lepi1_k3:
	s_mov_b64 s[6:7], s[50:51]
	v_pk_add_f32 v[172:173], v[126:127], v[202:203]
	v_pk_add_f32 v[174:175], v[128:129], v[204:205]
	v_pk_add_f32 v[176:177], v[122:123], v[206:207]
	v_pk_add_f32 v[178:179], v[124:125], v[208:209]
	v_pk_mul_f32 v[172:173], v[172:173], s[24:25] op_sel_hi:[1,0]
	v_pk_mul_f32 v[174:175], v[174:175], s[24:25] op_sel_hi:[1,0]
	v_pk_mul_f32 v[176:177], v[176:177], s[24:25] op_sel_hi:[1,0]
	v_pk_mul_f32 v[178:179], v[178:179], s[24:25] op_sel_hi:[1,0]
	v_exp_f32_e32 v172, v172
	v_exp_f32_e32 v173, v173
	v_exp_f32_e32 v174, v174
	v_exp_f32_e32 v175, v175
	v_exp_f32_e32 v176, v176
	v_exp_f32_e32 v177, v177
	v_exp_f32_e32 v178, v178
	v_exp_f32_e32 v179, v179
	v_pk_add_f32 v[172:173], v[172:173], 1.0 op_sel_hi:[1,0]
	v_pk_add_f32 v[174:175], v[174:175], 1.0 op_sel_hi:[1,0]
	v_pk_add_f32 v[176:177], v[176:177], 1.0 op_sel_hi:[1,0]
	v_pk_add_f32 v[178:179], v[178:179], 1.0 op_sel_hi:[1,0]
	v_rcp_f32_e32 v172, v172
	v_rcp_f32_e32 v173, v173
	v_rcp_f32_e32 v174, v174
	v_rcp_f32_e32 v175, v175
	v_rcp_f32_e32 v176, v176
	v_rcp_f32_e32 v177, v177
	v_rcp_f32_e32 v178, v178
	v_rcp_f32_e32 v179, v179
	v_cvt_pk_bf16_f32 v130, v172, v173
	v_cvt_pk_bf16_f32 v131, v174, v175
	v_cvt_pk_bf16_f32 v132, v176, v177
	v_cvt_pk_bf16_f32 v133, v178, v179
	global_store_dwordx4 v138, v[130:133], s[6:7] nt
	v_pk_add_f32 v[180:181], v[62:63], v[210:211]
	v_pk_add_f32 v[182:183], v[64:65], v[212:213]
	v_pk_add_f32 v[184:185], v[58:59], v[214:215]
	v_pk_add_f32 v[186:187], v[60:61], v[216:217]
	v_pk_mul_f32 v[180:181], v[180:181], s[24:25] op_sel_hi:[1,0]
	v_pk_mul_f32 v[182:183], v[182:183], s[24:25] op_sel_hi:[1,0]
	v_pk_mul_f32 v[184:185], v[184:185], s[24:25] op_sel_hi:[1,0]
	v_pk_mul_f32 v[186:187], v[186:187], s[24:25] op_sel_hi:[1,0]
	v_exp_f32_e32 v180, v180
	v_exp_f32_e32 v181, v181
	v_exp_f32_e32 v182, v182
	v_exp_f32_e32 v183, v183
	v_exp_f32_e32 v184, v184
	v_exp_f32_e32 v185, v185
	v_exp_f32_e32 v186, v186
	v_exp_f32_e32 v187, v187
	v_pk_add_f32 v[180:181], v[180:181], 1.0 op_sel_hi:[1,0]
	v_pk_add_f32 v[182:183], v[182:183], 1.0 op_sel_hi:[1,0]
	v_pk_add_f32 v[184:185], v[184:185], 1.0 op_sel_hi:[1,0]
	v_pk_add_f32 v[186:187], v[186:187], 1.0 op_sel_hi:[1,0]
	v_rcp_f32_e32 v180, v180
	v_rcp_f32_e32 v181, v181
	v_rcp_f32_e32 v182, v182
	v_rcp_f32_e32 v183, v183
	v_rcp_f32_e32 v184, v184
	v_rcp_f32_e32 v185, v185
	v_rcp_f32_e32 v186, v186
	v_rcp_f32_e32 v187, v187
	v_cvt_pk_bf16_f32 v134, v180, v181
	v_cvt_pk_bf16_f32 v135, v182, v183
	v_cvt_pk_bf16_f32 v136, v184, v185
	v_cvt_pk_bf16_f32 v137, v186, v187
	global_store_dwordx4 v138, v[134:137], s[6:7] offset:256 nt
	s_add_u32 s6, s6, 0x8000
	s_addc_u32 s7, s7, 0
	v_pk_add_f32 v[172:173], v[118:119], v[202:203]
	v_pk_add_f32 v[174:175], v[120:121], v[204:205]
	v_pk_add_f32 v[176:177], v[114:115], v[206:207]
	v_pk_add_f32 v[178:179], v[116:117], v[208:209]
	v_pk_mul_f32 v[172:173], v[172:173], s[24:25] op_sel_hi:[1,0]
	v_pk_mul_f32 v[174:175], v[174:175], s[24:25] op_sel_hi:[1,0]
	v_pk_mul_f32 v[176:177], v[176:177], s[24:25] op_sel_hi:[1,0]
	v_pk_mul_f32 v[178:179], v[178:179], s[24:25] op_sel_hi:[1,0]
	v_exp_f32_e32 v172, v172
	v_exp_f32_e32 v173, v173
	v_exp_f32_e32 v174, v174
	v_exp_f32_e32 v175, v175
	v_exp_f32_e32 v176, v176
	v_exp_f32_e32 v177, v177
	v_exp_f32_e32 v178, v178
	v_exp_f32_e32 v179, v179
	v_pk_add_f32 v[172:173], v[172:173], 1.0 op_sel_hi:[1,0]
	v_pk_add_f32 v[174:175], v[174:175], 1.0 op_sel_hi:[1,0]
	v_pk_add_f32 v[176:177], v[176:177], 1.0 op_sel_hi:[1,0]
	v_pk_add_f32 v[178:179], v[178:179], 1.0 op_sel_hi:[1,0]
	v_rcp_f32_e32 v172, v172
	v_rcp_f32_e32 v173, v173
	v_rcp_f32_e32 v174, v174
	v_rcp_f32_e32 v175, v175
	v_rcp_f32_e32 v176, v176
	v_rcp_f32_e32 v177, v177
	v_rcp_f32_e32 v178, v178
	v_rcp_f32_e32 v179, v179
	v_cvt_pk_bf16_f32 v140, v172, v173
	v_cvt_pk_bf16_f32 v141, v174, v175
	v_cvt_pk_bf16_f32 v142, v176, v177
	v_cvt_pk_bf16_f32 v143, v178, v179
	global_store_dwordx4 v138, v[140:143], s[6:7] nt
	v_pk_add_f32 v[180:181], v[54:55], v[210:211]
	v_pk_add_f32 v[182:183], v[56:57], v[212:213]
	v_pk_add_f32 v[184:185], v[50:51], v[214:215]
	v_pk_add_f32 v[186:187], v[52:53], v[216:217]
	v_pk_mul_f32 v[180:181], v[180:181], s[24:25] op_sel_hi:[1,0]
	v_pk_mul_f32 v[182:183], v[182:183], s[24:25] op_sel_hi:[1,0]
	v_pk_mul_f32 v[184:185], v[184:185], s[24:25] op_sel_hi:[1,0]
	v_pk_mul_f32 v[186:187], v[186:187], s[24:25] op_sel_hi:[1,0]
	v_exp_f32_e32 v180, v180
	v_exp_f32_e32 v181, v181
	v_exp_f32_e32 v182, v182
	v_exp_f32_e32 v183, v183
	v_exp_f32_e32 v184, v184
	v_exp_f32_e32 v185, v185
	v_exp_f32_e32 v186, v186
	v_exp_f32_e32 v187, v187
	v_pk_add_f32 v[180:181], v[180:181], 1.0 op_sel_hi:[1,0]
	v_pk_add_f32 v[182:183], v[182:183], 1.0 op_sel_hi:[1,0]
	v_pk_add_f32 v[184:185], v[184:185], 1.0 op_sel_hi:[1,0]
	v_pk_add_f32 v[186:187], v[186:187], 1.0 op_sel_hi:[1,0]
	v_rcp_f32_e32 v180, v180
	v_rcp_f32_e32 v181, v181
	v_rcp_f32_e32 v182, v182
	v_rcp_f32_e32 v183, v183
	v_rcp_f32_e32 v184, v184
	v_rcp_f32_e32 v185, v185
	v_rcp_f32_e32 v186, v186
	v_rcp_f32_e32 v187, v187
	v_cvt_pk_bf16_f32 v156, v180, v181
	v_cvt_pk_bf16_f32 v157, v182, v183
	v_cvt_pk_bf16_f32 v158, v184, v185
	v_cvt_pk_bf16_f32 v159, v186, v187
	global_store_dwordx4 v138, v[156:159], s[6:7] offset:256 nt
	s_add_u32 s6, s6, 0x8000
	s_addc_u32 s7, s7, 0
	v_pk_add_f32 v[172:173], v[110:111], v[202:203]
	v_pk_add_f32 v[174:175], v[112:113], v[204:205]
	v_pk_add_f32 v[176:177], v[106:107], v[206:207]
	v_pk_add_f32 v[178:179], v[108:109], v[208:209]
	v_pk_mul_f32 v[172:173], v[172:173], s[24:25] op_sel_hi:[1,0]
	v_pk_mul_f32 v[174:175], v[174:175], s[24:25] op_sel_hi:[1,0]
; __device__ __forceinline__ float sigm(float x) { return __builtin_amdgcn_rcpf(1.f + __expf(-x)); }
; __device__ __forceinline__ u32x4 pack8(const f32x4 v0, const f32x4 v1) { u32x4 w; w.x = cvt_pk_bf16(v0[0], v0[1]); w.y = cvt_pk_bf16(v0[2], v0[3]); w.z = cvt_pk_bf16(v1[0], v1[1]); w.w = cvt_pk_bf16(v1[2], v1[3]); return w; }
;     __device__ __forceinline__ void operator()(f32x4 (&acc)[2][2][4][2], const Unit& u, int wr, int wc, int fr, int fq) const {
;     ...
;             for (int ai = 0; ai < 2; ++ai)
; #pragma unroll
;                 for (int m = 0; m < 4; ++m) { bf16_t* rowp = base + (size_t)(ai * HALF + m * 16) * LDZ;
; #pragma unroll
;                     for (int bj = 0; bj < 2; ++bj) { f32x4 v0 = acc[ai][bj][m][0], v1 = acc[ai][bj][m][1];
;                         if (kind == 1) {
; #pragma unroll
;                             for (int e = 0; e < 4; ++e) { v0[e] = v0[e] * sigm(v0[e]); v1[e] = v1[e] * sigm(v1[e]); } }
;                         else if (kind == 2) { v0 = v0 * (0.125f * LOG2E); v1 = v1 * (0.125f * LOG2E); }
;                         else if (kind == 3) {
; #pragma unroll
;                             for (int e = 0; e < 4; ++e) { v0[e] = sigm(v0[e] + bv[bj][0][e]); v1[e] = sigm(v1[e] + bv[bj][1][e]); } }
;                         __builtin_nontemporal_store(pack8(v0, v1), (u32x4*)(rowp + bj * HALF)); } }
	v_pk_mul_f32 v[176:177], v[176:177], s[24:25] op_sel_hi:[1,0]
	v_pk_mul_f32 v[178:179], v[178:179], s[24:25] op_sel_hi:[1,0]
	v_exp_f32_e32 v172, v172
	v_exp_f32_e32 v173, v173
	v_exp_f32_e32 v174, v174
	v_exp_f32_e32 v175, v175
	v_exp_f32_e32 v176, v176
	v_exp_f32_e32 v177, v177
	v_exp_f32_e32 v178, v178
	v_exp_f32_e32 v179, v179
	v_pk_add_f32 v[172:173], v[172:173], 1.0 op_sel_hi:[1,0]
	v_pk_add_f32 v[174:175], v[174:175], 1.0 op_sel_hi:[1,0]
	v_pk_add_f32 v[176:177], v[176:177], 1.0 op_sel_hi:[1,0]
	v_pk_add_f32 v[178:179], v[178:179], 1.0 op_sel_hi:[1,0]
	v_rcp_f32_e32 v172, v172
	v_rcp_f32_e32 v173, v173
	v_rcp_f32_e32 v174, v174
	v_rcp_f32_e32 v175, v175
	v_rcp_f32_e32 v176, v176
	v_rcp_f32_e32 v177, v177
	v_rcp_f32_e32 v178, v178
	v_rcp_f32_e32 v179, v179
	v_cvt_pk_bf16_f32 v130, v172, v173
	v_cvt_pk_bf16_f32 v131, v174, v175
	v_cvt_pk_bf16_f32 v132, v176, v177
	v_cvt_pk_bf16_f32 v133, v178, v179
	global_store_dwordx4 v138, v[130:133], s[6:7] nt
	v_pk_add_f32 v[180:181], v[46:47], v[210:211]
	v_pk_add_f32 v[182:183], v[48:49], v[212:213]
	v_pk_add_f32 v[184:185], v[42:43], v[214:215]
	v_pk_add_f32 v[186:187], v[44:45], v[216:217]
	v_pk_mul_f32 v[180:181], v[180:181], s[24:25] op_sel_hi:[1,0]
	v_pk_mul_f32 v[182:183], v[182:183], s[24:25] op_sel_hi:[1,0]
	v_pk_mul_f32 v[184:185], v[184:185], s[24:25] op_sel_hi:[1,0]
	v_pk_mul_f32 v[186:187], v[186:187], s[24:25] op_sel_hi:[1,0]
	v_exp_f32_e32 v180, v180
	v_exp_f32_e32 v181, v181
	v_exp_f32_e32 v182, v182
	v_exp_f32_e32 v183, v183
	v_exp_f32_e32 v184, v184
	v_exp_f32_e32 v185, v185
	v_exp_f32_e32 v186, v186
	v_exp_f32_e32 v187, v187
	v_pk_add_f32 v[180:181], v[180:181], 1.0 op_sel_hi:[1,0]
	v_pk_add_f32 v[182:183], v[182:183], 1.0 op_sel_hi:[1,0]
	v_pk_add_f32 v[184:185], v[184:185], 1.0 op_sel_hi:[1,0]
	v_pk_add_f32 v[186:187], v[186:187], 1.0 op_sel_hi:[1,0]
	v_rcp_f32_e32 v180, v180
	v_rcp_f32_e32 v181, v181
	v_rcp_f32_e32 v182, v182
	v_rcp_f32_e32 v183, v183
	v_rcp_f32_e32 v184, v184
	v_rcp_f32_e32 v185, v185
	v_rcp_f32_e32 v186, v186
	v_rcp_f32_e32 v187, v187
	v_cvt_pk_bf16_f32 v134, v180, v181
	v_cvt_pk_bf16_f32 v135, v182, v183
	v_cvt_pk_bf16_f32 v136, v184, v185
	v_cvt_pk_bf16_f32 v137, v186, v187
	global_store_dwordx4 v138, v[134:137], s[6:7] offset:256 nt
	s_add_u32 s6, s6, 0x8000
	s_addc_u32 s7, s7, 0
	v_pk_add_f32 v[172:173], v[102:103], v[202:203]
	v_pk_add_f32 v[174:175], v[104:105], v[204:205]
	v_pk_add_f32 v[176:177], v[98:99], v[206:207]
	v_pk_add_f32 v[178:179], v[100:101], v[208:209]
	v_pk_mul_f32 v[172:173], v[172:173], s[24:25] op_sel_hi:[1,0]
	v_pk_mul_f32 v[174:175], v[174:175], s[24:25] op_sel_hi:[1,0]
	v_pk_mul_f32 v[176:177], v[176:177], s[24:25] op_sel_hi:[1,0]
	v_pk_mul_f32 v[178:179], v[178:179], s[24:25] op_sel_hi:[1,0]
	v_exp_f32_e32 v172, v172
	v_exp_f32_e32 v173, v173
	v_exp_f32_e32 v174, v174
	v_exp_f32_e32 v175, v175
	v_exp_f32_e32 v176, v176
	v_exp_f32_e32 v177, v177
	v_exp_f32_e32 v178, v178
	v_exp_f32_e32 v179, v179
	v_pk_add_f32 v[172:173], v[172:173], 1.0 op_sel_hi:[1,0]
	v_pk_add_f32 v[174:175], v[174:175], 1.0 op_sel_hi:[1,0]
	v_pk_add_f32 v[176:177], v[176:177], 1.0 op_sel_hi:[1,0]
	v_pk_add_f32 v[178:179], v[178:179], 1.0 op_sel_hi:[1,0]
	v_rcp_f32_e32 v172, v172
	v_rcp_f32_e32 v173, v173
	v_rcp_f32_e32 v174, v174
	v_rcp_f32_e32 v175, v175
	v_rcp_f32_e32 v176, v176
	v_rcp_f32_e32 v177, v177
	v_rcp_f32_e32 v178, v178
	v_rcp_f32_e32 v179, v179
	v_cvt_pk_bf16_f32 v140, v172, v173
	v_cvt_pk_bf16_f32 v141, v174, v175
	v_cvt_pk_bf16_f32 v142, v176, v177
	v_cvt_pk_bf16_f32 v143, v178, v179
	global_store_dwordx4 v138, v[140:143], s[6:7] nt
	v_pk_add_f32 v[180:181], v[38:39], v[210:211]
	v_pk_add_f32 v[182:183], v[40:41], v[212:213]
	v_pk_add_f32 v[184:185], v[34:35], v[214:215]
	v_pk_add_f32 v[186:187], v[36:37], v[216:217]
	v_pk_mul_f32 v[180:181], v[180:181], s[24:25] op_sel_hi:[1,0]
	v_pk_mul_f32 v[182:183], v[182:183], s[24:25] op_sel_hi:[1,0]
	v_pk_mul_f32 v[184:185], v[184:185], s[24:25] op_sel_hi:[1,0]
	v_pk_mul_f32 v[186:187], v[186:187], s[24:25] op_sel_hi:[1,0]
	v_exp_f32_e32 v180, v180
	v_exp_f32_e32 v181, v181
	v_exp_f32_e32 v182, v182
	v_exp_f32_e32 v183, v183
	v_exp_f32_e32 v184, v184
	v_exp_f32_e32 v185, v185
	v_exp_f32_e32 v186, v186
	v_exp_f32_e32 v187, v187
	v_pk_add_f32 v[180:181], v[180:181], 1.0 op_sel_hi:[1,0]
	v_pk_add_f32 v[182:183], v[182:183], 1.0 op_sel_hi:[1,0]
	v_pk_add_f32 v[184:185], v[184:185], 1.0 op_sel_hi:[1,0]
	v_pk_add_f32 v[186:187], v[186:187], 1.0 op_sel_hi:[1,0]
	v_rcp_f32_e32 v180, v180
	v_rcp_f32_e32 v181, v181
	v_rcp_f32_e32 v182, v182
	v_rcp_f32_e32 v183, v183
	v_rcp_f32_e32 v184, v184
	v_rcp_f32_e32 v185, v185
	v_rcp_f32_e32 v186, v186
	v_rcp_f32_e32 v187, v187
	v_cvt_pk_bf16_f32 v156, v180, v181
	v_cvt_pk_bf16_f32 v157, v182, v183
	v_cvt_pk_bf16_f32 v158, v184, v185
	v_cvt_pk_bf16_f32 v159, v186, v187
	global_store_dwordx4 v138, v[156:159], s[6:7] offset:256 nt
	s_add_u32 s6, s6, 0x28000
	s_addc_u32 s7, s7, 0
	v_pk_add_f32 v[172:173], v[94:95], v[202:203]
	v_pk_add_f32 v[174:175], v[96:97], v[204:205]
	v_pk_add_f32 v[176:177], v[90:91], v[206:207]
	v_pk_add_f32 v[178:179], v[92:93], v[208:209]
	v_pk_mul_f32 v[172:173], v[172:173], s[24:25] op_sel_hi:[1,0]
	v_pk_mul_f32 v[174:175], v[174:175], s[24:25] op_sel_hi:[1,0]
	v_pk_mul_f32 v[176:177], v[176:177], s[24:25] op_sel_hi:[1,0]
	v_pk_mul_f32 v[178:179], v[178:179], s[24:25] op_sel_hi:[1,0]
	v_exp_f32_e32 v172, v172
	v_exp_f32_e32 v173, v173
	v_exp_f32_e32 v174, v174
	v_exp_f32_e32 v175, v175
	v_exp_f32_e32 v176, v176
	v_exp_f32_e32 v177, v177
	v_exp_f32_e32 v178, v178
	v_exp_f32_e32 v179, v179
	v_pk_add_f32 v[172:173], v[172:173], 1.0 op_sel_hi:[1,0]
; __device__ __forceinline__ float sigm(float x) { return __builtin_amdgcn_rcpf(1.f + __expf(-x)); }
; __device__ __forceinline__ u32x4 pack8(const f32x4 v0, const f32x4 v1) { u32x4 w; w.x = cvt_pk_bf16(v0[0], v0[1]); w.y = cvt_pk_bf16(v0[2], v0[3]); w.z = cvt_pk_bf16(v1[0], v1[1]); w.w = cvt_pk_bf16(v1[2], v1[3]); return w; }
;     __device__ __forceinline__ void operator()(f32x4 (&acc)[2][2][4][2], const Unit& u, int wr, int wc, int fr, int fq) const {
;     ...
;             for (int ai = 0; ai < 2; ++ai)
; #pragma unroll
;                 for (int m = 0; m < 4; ++m) { bf16_t* rowp = base + (size_t)(ai * HALF + m * 16) * LDZ;
; #pragma unroll
;                     for (int bj = 0; bj < 2; ++bj) { f32x4 v0 = acc[ai][bj][m][0], v1 = acc[ai][bj][m][1];
;                         if (kind == 1) {
; #pragma unroll
;                             for (int e = 0; e < 4; ++e) { v0[e] = v0[e] * sigm(v0[e]); v1[e] = v1[e] * sigm(v1[e]); } }
;                         else if (kind == 2) { v0 = v0 * (0.125f * LOG2E); v1 = v1 * (0.125f * LOG2E); }
;                         else if (kind == 3) {
; #pragma unroll
;                             for (int e = 0; e < 4; ++e) { v0[e] = sigm(v0[e] + bv[bj][0][e]); v1[e] = sigm(v1[e] + bv[bj][1][e]); } }
;                         __builtin_nontemporal_store(pack8(v0, v1), (u32x4*)(rowp + bj * HALF)); } }
	v_pk_add_f32 v[174:175], v[174:175], 1.0 op_sel_hi:[1,0]
	v_pk_add_f32 v[176:177], v[176:177], 1.0 op_sel_hi:[1,0]
	v_pk_add_f32 v[178:179], v[178:179], 1.0 op_sel_hi:[1,0]
	v_rcp_f32_e32 v172, v172
	v_rcp_f32_e32 v173, v173
	v_rcp_f32_e32 v174, v174
	v_rcp_f32_e32 v175, v175
	v_rcp_f32_e32 v176, v176
	v_rcp_f32_e32 v177, v177
	v_rcp_f32_e32 v178, v178
	v_rcp_f32_e32 v179, v179
	v_cvt_pk_bf16_f32 v130, v172, v173
	v_cvt_pk_bf16_f32 v131, v174, v175
	v_cvt_pk_bf16_f32 v132, v176, v177
	v_cvt_pk_bf16_f32 v133, v178, v179
	global_store_dwordx4 v138, v[130:133], s[6:7] nt
	v_pk_add_f32 v[180:181], v[30:31], v[210:211]
	v_pk_add_f32 v[182:183], v[32:33], v[212:213]
	v_pk_add_f32 v[184:185], v[26:27], v[214:215]
	v_pk_add_f32 v[186:187], v[28:29], v[216:217]
	v_pk_mul_f32 v[180:181], v[180:181], s[24:25] op_sel_hi:[1,0]
	v_pk_mul_f32 v[182:183], v[182:183], s[24:25] op_sel_hi:[1,0]
	v_pk_mul_f32 v[184:185], v[184:185], s[24:25] op_sel_hi:[1,0]
	v_pk_mul_f32 v[186:187], v[186:187], s[24:25] op_sel_hi:[1,0]
	v_exp_f32_e32 v180, v180
	v_exp_f32_e32 v181, v181
	v_exp_f32_e32 v182, v182
	v_exp_f32_e32 v183, v183
	v_exp_f32_e32 v184, v184
	v_exp_f32_e32 v185, v185
	v_exp_f32_e32 v186, v186
	v_exp_f32_e32 v187, v187
	v_pk_add_f32 v[180:181], v[180:181], 1.0 op_sel_hi:[1,0]
	v_pk_add_f32 v[182:183], v[182:183], 1.0 op_sel_hi:[1,0]
	v_pk_add_f32 v[184:185], v[184:185], 1.0 op_sel_hi:[1,0]
	v_pk_add_f32 v[186:187], v[186:187], 1.0 op_sel_hi:[1,0]
	v_rcp_f32_e32 v180, v180
	v_rcp_f32_e32 v181, v181
	v_rcp_f32_e32 v182, v182
	v_rcp_f32_e32 v183, v183
	v_rcp_f32_e32 v184, v184
	v_rcp_f32_e32 v185, v185
	v_rcp_f32_e32 v186, v186
	v_rcp_f32_e32 v187, v187
	v_cvt_pk_bf16_f32 v134, v180, v181
	v_cvt_pk_bf16_f32 v135, v182, v183
	v_cvt_pk_bf16_f32 v136, v184, v185
	v_cvt_pk_bf16_f32 v137, v186, v187
	global_store_dwordx4 v138, v[134:137], s[6:7] offset:256 nt
	s_add_u32 s6, s6, 0x8000
	s_addc_u32 s7, s7, 0
	v_pk_add_f32 v[172:173], v[86:87], v[202:203]
	v_pk_add_f32 v[174:175], v[88:89], v[204:205]
	v_pk_add_f32 v[176:177], v[82:83], v[206:207]
	v_pk_add_f32 v[178:179], v[84:85], v[208:209]
	v_pk_mul_f32 v[172:173], v[172:173], s[24:25] op_sel_hi:[1,0]
	v_pk_mul_f32 v[174:175], v[174:175], s[24:25] op_sel_hi:[1,0]
	v_pk_mul_f32 v[176:177], v[176:177], s[24:25] op_sel_hi:[1,0]
	v_pk_mul_f32 v[178:179], v[178:179], s[24:25] op_sel_hi:[1,0]
	v_exp_f32_e32 v172, v172
	v_exp_f32_e32 v173, v173
	v_exp_f32_e32 v174, v174
	v_exp_f32_e32 v175, v175
	v_exp_f32_e32 v176, v176
	v_exp_f32_e32 v177, v177
	v_exp_f32_e32 v178, v178
	v_exp_f32_e32 v179, v179
	v_pk_add_f32 v[172:173], v[172:173], 1.0 op_sel_hi:[1,0]
	v_pk_add_f32 v[174:175], v[174:175], 1.0 op_sel_hi:[1,0]
	v_pk_add_f32 v[176:177], v[176:177], 1.0 op_sel_hi:[1,0]
	v_pk_add_f32 v[178:179], v[178:179], 1.0 op_sel_hi:[1,0]
	v_rcp_f32_e32 v172, v172
	v_rcp_f32_e32 v173, v173
	v_rcp_f32_e32 v174, v174
	v_rcp_f32_e32 v175, v175
	v_rcp_f32_e32 v176, v176
	v_rcp_f32_e32 v177, v177
	v_rcp_f32_e32 v178, v178
	v_rcp_f32_e32 v179, v179
	v_cvt_pk_bf16_f32 v140, v172, v173
	v_cvt_pk_bf16_f32 v141, v174, v175
	v_cvt_pk_bf16_f32 v142, v176, v177
	v_cvt_pk_bf16_f32 v143, v178, v179
	global_store_dwordx4 v138, v[140:143], s[6:7] nt
	v_pk_add_f32 v[180:181], v[22:23], v[210:211]
	v_pk_add_f32 v[182:183], v[24:25], v[212:213]
	v_pk_add_f32 v[184:185], v[18:19], v[214:215]
	v_pk_add_f32 v[186:187], v[20:21], v[216:217]
	v_pk_mul_f32 v[180:181], v[180:181], s[24:25] op_sel_hi:[1,0]
	v_pk_mul_f32 v[182:183], v[182:183], s[24:25] op_sel_hi:[1,0]
	v_pk_mul_f32 v[184:185], v[184:185], s[24:25] op_sel_hi:[1,0]
	v_pk_mul_f32 v[186:187], v[186:187], s[24:25] op_sel_hi:[1,0]
	v_exp_f32_e32 v180, v180
	v_exp_f32_e32 v181, v181
	v_exp_f32_e32 v182, v182
	v_exp_f32_e32 v183, v183
	v_exp_f32_e32 v184, v184
	v_exp_f32_e32 v185, v185
	v_exp_f32_e32 v186, v186
	v_exp_f32_e32 v187, v187
	v_pk_add_f32 v[180:181], v[180:181], 1.0 op_sel_hi:[1,0]
	v_pk_add_f32 v[182:183], v[182:183], 1.0 op_sel_hi:[1,0]
	v_pk_add_f32 v[184:185], v[184:185], 1.0 op_sel_hi:[1,0]
	v_pk_add_f32 v[186:187], v[186:187], 1.0 op_sel_hi:[1,0]
	v_rcp_f32_e32 v180, v180
	v_rcp_f32_e32 v181, v181
	v_rcp_f32_e32 v182, v182
	v_rcp_f32_e32 v183, v183
	v_rcp_f32_e32 v184, v184
	v_rcp_f32_e32 v185, v185
	v_rcp_f32_e32 v186, v186
	v_rcp_f32_e32 v187, v187
	v_cvt_pk_bf16_f32 v156, v180, v181
	v_cvt_pk_bf16_f32 v157, v182, v183
	v_cvt_pk_bf16_f32 v158, v184, v185
	v_cvt_pk_bf16_f32 v159, v186, v187
	global_store_dwordx4 v138, v[156:159], s[6:7] offset:256 nt
	s_add_u32 s6, s6, 0x8000
	s_addc_u32 s7, s7, 0
	v_pk_add_f32 v[172:173], v[78:79], v[202:203]
	v_pk_add_f32 v[174:175], v[80:81], v[204:205]
	v_pk_add_f32 v[176:177], v[74:75], v[206:207]
	v_pk_add_f32 v[178:179], v[76:77], v[208:209]
	v_pk_mul_f32 v[172:173], v[172:173], s[24:25] op_sel_hi:[1,0]
	v_pk_mul_f32 v[174:175], v[174:175], s[24:25] op_sel_hi:[1,0]
	v_pk_mul_f32 v[176:177], v[176:177], s[24:25] op_sel_hi:[1,0]
	v_pk_mul_f32 v[178:179], v[178:179], s[24:25] op_sel_hi:[1,0]
	v_exp_f32_e32 v172, v172
	v_exp_f32_e32 v173, v173
	v_exp_f32_e32 v174, v174
	v_exp_f32_e32 v175, v175
	v_exp_f32_e32 v176, v176
	v_exp_f32_e32 v177, v177
	v_exp_f32_e32 v178, v178
	v_exp_f32_e32 v179, v179
	v_pk_add_f32 v[172:173], v[172:173], 1.0 op_sel_hi:[1,0]
	v_pk_add_f32 v[174:175], v[174:175], 1.0 op_sel_hi:[1,0]
	v_pk_add_f32 v[176:177], v[176:177], 1.0 op_sel_hi:[1,0]
	v_pk_add_f32 v[178:179], v[178:179], 1.0 op_sel_hi:[1,0]
	v_rcp_f32_e32 v172, v172
	v_rcp_f32_e32 v173, v173
	v_rcp_f32_e32 v174, v174
	v_rcp_f32_e32 v175, v175
	v_rcp_f32_e32 v176, v176
	v_rcp_f32_e32 v177, v177
	v_rcp_f32_e32 v178, v178
	v_rcp_f32_e32 v179, v179
; __device__ __forceinline__ float sigm(float x) { return __builtin_amdgcn_rcpf(1.f + __expf(-x)); }
; __device__ __forceinline__ u32x4 pack8(const f32x4 v0, const f32x4 v1) { u32x4 w; w.x = cvt_pk_bf16(v0[0], v0[1]); w.y = cvt_pk_bf16(v0[2], v0[3]); w.z = cvt_pk_bf16(v1[0], v1[1]); w.w = cvt_pk_bf16(v1[2], v1[3]); return w; }
;     __device__ __forceinline__ void operator()(f32x4 (&acc)[2][2][4][2], const Unit& u, int wr, int wc, int fr, int fq) const {
;     ...
;             for (int ai = 0; ai < 2; ++ai)
; #pragma unroll
;                 for (int m = 0; m < 4; ++m) { bf16_t* rowp = base + (size_t)(ai * HALF + m * 16) * LDZ;
; #pragma unroll
;                     for (int bj = 0; bj < 2; ++bj) { f32x4 v0 = acc[ai][bj][m][0], v1 = acc[ai][bj][m][1];
;                         if (kind == 1) {
; #pragma unroll
;                             for (int e = 0; e < 4; ++e) { v0[e] = v0[e] * sigm(v0[e]); v1[e] = v1[e] * sigm(v1[e]); } }
;                         else if (kind == 2) { v0 = v0 * (0.125f * LOG2E); v1 = v1 * (0.125f * LOG2E); }
;                         else if (kind == 3) {
; #pragma unroll
;                             for (int e = 0; e < 4; ++e) { v0[e] = sigm(v0[e] + bv[bj][0][e]); v1[e] = sigm(v1[e] + bv[bj][1][e]); } }
;                         __builtin_nontemporal_store(pack8(v0, v1), (u32x4*)(rowp + bj * HALF)); } }
	v_cvt_pk_bf16_f32 v130, v172, v173
	v_cvt_pk_bf16_f32 v131, v174, v175
	v_cvt_pk_bf16_f32 v132, v176, v177
	v_cvt_pk_bf16_f32 v133, v178, v179
	global_store_dwordx4 v138, v[130:133], s[6:7] nt
	v_pk_add_f32 v[180:181], v[14:15], v[210:211]
	v_pk_add_f32 v[182:183], v[16:17], v[212:213]
	v_pk_add_f32 v[184:185], v[10:11], v[214:215]
	v_pk_add_f32 v[186:187], v[12:13], v[216:217]
	v_pk_mul_f32 v[180:181], v[180:181], s[24:25] op_sel_hi:[1,0]
	v_pk_mul_f32 v[182:183], v[182:183], s[24:25] op_sel_hi:[1,0]
	v_pk_mul_f32 v[184:185], v[184:185], s[24:25] op_sel_hi:[1,0]
	v_pk_mul_f32 v[186:187], v[186:187], s[24:25] op_sel_hi:[1,0]
	v_exp_f32_e32 v180, v180
	v_exp_f32_e32 v181, v181
	v_exp_f32_e32 v182, v182
	v_exp_f32_e32 v183, v183
	v_exp_f32_e32 v184, v184
	v_exp_f32_e32 v185, v185
	v_exp_f32_e32 v186, v186
	v_exp_f32_e32 v187, v187
	v_pk_add_f32 v[180:181], v[180:181], 1.0 op_sel_hi:[1,0]
	v_pk_add_f32 v[182:183], v[182:183], 1.0 op_sel_hi:[1,0]
	v_pk_add_f32 v[184:185], v[184:185], 1.0 op_sel_hi:[1,0]
	v_pk_add_f32 v[186:187], v[186:187], 1.0 op_sel_hi:[1,0]
	v_rcp_f32_e32 v180, v180
	v_rcp_f32_e32 v181, v181
	v_rcp_f32_e32 v182, v182
	v_rcp_f32_e32 v183, v183
	v_rcp_f32_e32 v184, v184
	v_rcp_f32_e32 v185, v185
	v_rcp_f32_e32 v186, v186
	v_rcp_f32_e32 v187, v187
	v_cvt_pk_bf16_f32 v134, v180, v181
	v_cvt_pk_bf16_f32 v135, v182, v183
	v_cvt_pk_bf16_f32 v136, v184, v185
	v_cvt_pk_bf16_f32 v137, v186, v187
	global_store_dwordx4 v138, v[134:137], s[6:7] offset:256 nt
	s_add_u32 s6, s6, 0x8000
	s_addc_u32 s7, s7, 0
	v_pk_add_f32 v[172:173], v[70:71], v[202:203]
	v_pk_add_f32 v[174:175], v[72:73], v[204:205]
	v_pk_add_f32 v[176:177], v[66:67], v[206:207]
	v_pk_add_f32 v[178:179], v[68:69], v[208:209]
	v_pk_mul_f32 v[172:173], v[172:173], s[24:25] op_sel_hi:[1,0]
	v_pk_mul_f32 v[174:175], v[174:175], s[24:25] op_sel_hi:[1,0]
	v_pk_mul_f32 v[176:177], v[176:177], s[24:25] op_sel_hi:[1,0]
	v_pk_mul_f32 v[178:179], v[178:179], s[24:25] op_sel_hi:[1,0]
	v_exp_f32_e32 v172, v172
	v_exp_f32_e32 v173, v173
	v_exp_f32_e32 v174, v174
	v_exp_f32_e32 v175, v175
	v_exp_f32_e32 v176, v176
	v_exp_f32_e32 v177, v177
	v_exp_f32_e32 v178, v178
	v_exp_f32_e32 v179, v179
	v_pk_add_f32 v[172:173], v[172:173], 1.0 op_sel_hi:[1,0]
	v_pk_add_f32 v[174:175], v[174:175], 1.0 op_sel_hi:[1,0]
	v_pk_add_f32 v[176:177], v[176:177], 1.0 op_sel_hi:[1,0]
	v_pk_add_f32 v[178:179], v[178:179], 1.0 op_sel_hi:[1,0]
	v_rcp_f32_e32 v172, v172
	v_rcp_f32_e32 v173, v173
	v_rcp_f32_e32 v174, v174
	v_rcp_f32_e32 v175, v175
	v_rcp_f32_e32 v176, v176
	v_rcp_f32_e32 v177, v177
	v_rcp_f32_e32 v178, v178
	v_rcp_f32_e32 v179, v179
	v_cvt_pk_bf16_f32 v140, v172, v173
	v_cvt_pk_bf16_f32 v141, v174, v175
	v_cvt_pk_bf16_f32 v142, v176, v177
	v_cvt_pk_bf16_f32 v143, v178, v179
	global_store_dwordx4 v138, v[140:143], s[6:7] nt
	v_pk_add_f32 v[180:181], v[6:7], v[210:211]
	v_pk_add_f32 v[182:183], v[8:9], v[212:213]
	v_pk_add_f32 v[184:185], v[2:3], v[214:215]
	v_pk_add_f32 v[186:187], v[4:5], v[216:217]
	v_pk_mul_f32 v[180:181], v[180:181], s[24:25] op_sel_hi:[1,0]
	v_pk_mul_f32 v[182:183], v[182:183], s[24:25] op_sel_hi:[1,0]
	v_pk_mul_f32 v[184:185], v[184:185], s[24:25] op_sel_hi:[1,0]
	v_pk_mul_f32 v[186:187], v[186:187], s[24:25] op_sel_hi:[1,0]
	v_exp_f32_e32 v180, v180
	v_exp_f32_e32 v181, v181
	v_exp_f32_e32 v182, v182
	v_exp_f32_e32 v183, v183
	v_exp_f32_e32 v184, v184
	v_exp_f32_e32 v185, v185
	v_exp_f32_e32 v186, v186
	v_exp_f32_e32 v187, v187
	v_pk_add_f32 v[180:181], v[180:181], 1.0 op_sel_hi:[1,0]
	v_pk_add_f32 v[182:183], v[182:183], 1.0 op_sel_hi:[1,0]
	v_pk_add_f32 v[184:185], v[184:185], 1.0 op_sel_hi:[1,0]
	v_pk_add_f32 v[186:187], v[186:187], 1.0 op_sel_hi:[1,0]
	v_rcp_f32_e32 v180, v180
	v_rcp_f32_e32 v181, v181
	v_rcp_f32_e32 v182, v182
	v_rcp_f32_e32 v183, v183
	v_rcp_f32_e32 v184, v184
	v_rcp_f32_e32 v185, v185
	v_rcp_f32_e32 v186, v186
	v_rcp_f32_e32 v187, v187
	v_cvt_pk_bf16_f32 v156, v180, v181
	v_cvt_pk_bf16_f32 v157, v182, v183
	v_cvt_pk_bf16_f32 v158, v184, v185
	v_cvt_pk_bf16_f32 v159, v186, v187
	global_store_dwordx4 v138, v[156:159], s[6:7] offset:256 nt
	s_branch .Lepi1_done
; __device__ __forceinline__ float shx(float v, int lane, int m) { return __builtin_bit_cast(float, __builtin_amdgcn_ds_bpermute((lane ^ m) << 2, __builtin_bit_cast(int, v))); }
;     __device__ __forceinline__ void operator()(f32x4 (&acc)[2][2][4][2], const Unit& u, int wr, int wc, int fr, int fq) const {
;     ...
;             if (pn >= 8 && pn < 16) {
;                 const float sc2 = (pn < 12) ? (0.125f * LOG2E) * (0.125f * LOG2E) : 1.f;
;                 const int tokb = tok0 + u.pm * BM, bg = tokb >> 13, qb = (tokb & (T - 1)) >> 8;
; #pragma unroll
;                 for (int bj = 0; bj < 2; ++bj) { float mx = 0.f;
; #pragma unroll
;                     for (int ai = 0; ai < 2; ++ai)
; #pragma unroll
;                         for (int m = 0; m < 4; ++m) { const f32x4 v0 = acc[ai][bj][m][0], v1 = acc[ai][bj][m][1];
;                             float q = (v0[0] * v0[0] + v0[1] * v0[1]) + (v0[2] * v0[2] + v0[3] * v0[3]) + (v1[0] * v1[0] + v1[1] * v1[1]) + (v1[2] * v1[2] + v1[3] * v1[3]);
;                             q += shx(q, lane_, 16); q += shx(q, lane_, 32); mx = fmaxf(mx, q); }
;                     mx = fmaxf(mx, shx(mx, lane_, 1)); mx = fmaxf(mx, shx(mx, lane_, 2)); mx = fmaxf(mx, shx(mx, lane_, 4)); mx = fmaxf(mx, shx(mx, lane_, 8));
;                     if (lane_ == 0) { const int head = (pn & 3) * 4 + 2 * bj + (wc >> 1), half = wc & 1;
;                         unsigned* w = (pn < 12) ? NRM + 1024 + ((bg * 16 + head) * 32 + qb) * 2 + half : NRM + (bg * 16 + head) * 2 + half;
;                         __hip_atomic_fetch_max(w, __builtin_bit_cast(unsigned, mx * sc2 * 1.02f), __ATOMIC_RELAXED, __HIP_MEMORY_SCOPE_AGENT); } }
.Lepi1_done:
	s_and_b32 s2, s56, -8
	s_cmp_lg_u32 s2, 8
	s_cbranch_scc1 .LBB0_346
	v_mul_f32_e32 v127, v127, v127
	v_mul_f32_e32 v119, v119, v119
	v_fmac_f32_e32 v127, v126, v126
	v_mul_f32_e32 v126, v129, v129
	v_fmac_f32_e32 v119, v118, v118
	v_mul_f32_e32 v118, v121, v121
	v_mul_f32_e32 v111, v111, v111
	v_mul_f32_e32 v103, v103, v103
	v_fmac_f32_e32 v126, v128, v128
	v_mul_f32_e32 v123, v123, v123
	v_fmac_f32_e32 v118, v120, v120
	v_mul_f32_e32 v115, v115, v115
	v_fmac_f32_e32 v111, v110, v110
	v_mul_f32_e32 v110, v113, v113
	v_fmac_f32_e32 v103, v102, v102
	v_mul_f32_e32 v102, v105, v105
	v_mul_f32_e32 v95, v95, v95
	v_mul_f32_e32 v87, v87, v87
	v_add_f32_e32 v126, v127, v126
	v_fmac_f32_e32 v123, v122, v122
	v_add_f32_e32 v118, v119, v118
	v_fmac_f32_e32 v115, v114, v114
	v_fmac_f32_e32 v110, v112, v112
	v_mul_f32_e32 v107, v107, v107
	v_fmac_f32_e32 v102, v104, v104
	v_mul_f32_e32 v99, v99, v99
	v_fmac_f32_e32 v95, v94, v94
	v_mul_f32_e32 v94, v97, v97
	v_fmac_f32_e32 v87, v86, v86
	v_mul_f32_e32 v86, v89, v89
	v_mul_f32_e32 v79, v79, v79
	v_mul_f32_e32 v71, v71, v71
	v_lshl_add_u32 v131, v171, 4, v170
	v_add_f32_e32 v122, v126, v123
	v_mul_f32_e32 v123, v125, v125
	v_add_f32_e32 v114, v118, v115
	v_mul_f32_e32 v115, v117, v117
	v_add_f32_e32 v110, v111, v110
	v_fmac_f32_e32 v107, v106, v106
	v_add_f32_e32 v102, v103, v102
	v_fmac_f32_e32 v99, v98, v98
	v_fmac_f32_e32 v94, v96, v96
	v_mul_f32_e32 v91, v91, v91
	v_fmac_f32_e32 v86, v88, v88
	v_mul_f32_e32 v83, v83, v83
	v_fmac_f32_e32 v79, v78, v78
	v_mul_f32_e32 v78, v81, v81
	v_fmac_f32_e32 v71, v70, v70
	v_mul_f32_e32 v70, v73, v73
	v_lshlrev_b32_e32 v132, 2, v131
	v_fmac_f32_e32 v123, v124, v124
	v_fmac_f32_e32 v115, v116, v116
	v_add_f32_e32 v106, v110, v107
	v_mul_f32_e32 v107, v109, v109
	v_add_f32_e32 v98, v102, v99
	v_mul_f32_e32 v99, v101, v101
	v_add_f32_e32 v94, v95, v94
	v_fmac_f32_e32 v91, v90, v90
	v_add_f32_e32 v86, v87, v86
	v_fmac_f32_e32 v83, v82, v82
	v_fmac_f32_e32 v78, v80, v80
	v_mul_f32_e32 v75, v75, v75
	v_fmac_f32_e32 v70, v72, v72
	v_mul_f32_e32 v67, v67, v67
	v_xor_b32_e32 v130, 64, v132
	v_add_f32_e32 v122, v123, v122
	v_add_f32_e32 v116, v115, v114
	v_fmac_f32_e32 v107, v108, v108
	v_fmac_f32_e32 v99, v100, v100
	v_add_f32_e32 v90, v94, v91
	v_mul_f32_e32 v91, v93, v93
	v_add_f32_e32 v82, v86, v83
	v_mul_f32_e32 v83, v85, v85
	v_add_f32_e32 v78, v79, v78
	v_fmac_f32_e32 v75, v74, v74
	v_add_f32_e32 v70, v71, v70
	v_fmac_f32_e32 v67, v66, v66
	ds_bpermute_b32 v123, v130, v122
	ds_bpermute_b32 v117, v130, v116
	v_add_f32_e32 v106, v107, v106
	v_add_f32_e32 v98, v99, v98
	v_fmac_f32_e32 v91, v92, v92
	v_fmac_f32_e32 v83, v84, v84
	v_add_f32_e32 v74, v78, v75
	v_mul_f32_e32 v75, v77, v77
	v_add_f32_e32 v66, v70, v67
	v_mul_f32_e32 v67, v69, v69
	ds_bpermute_b32 v107, v130, v106
	ds_bpermute_b32 v99, v130, v98
	v_add_f32_e32 v90, v91, v90
	v_add_f32_e32 v82, v83, v82
	v_fmac_f32_e32 v75, v76, v76
	v_fmac_f32_e32 v67, v68, v68
	ds_bpermute_b32 v91, v130, v90
	ds_bpermute_b32 v83, v130, v82
	v_add_f32_e32 v74, v75, v74
	v_add_f32_e32 v66, v67, v66
	ds_bpermute_b32 v75, v130, v74
	ds_bpermute_b32 v67, v130, v66
	v_xor_b32_e32 v115, 0x80, v132
	s_waitcnt lgkmcnt(7)
	v_add_f32_e32 v118, v122, v123
	s_waitcnt lgkmcnt(6)
	v_add_f32_e32 v116, v116, v117
	ds_bpermute_b32 v119, v115, v118
	ds_bpermute_b32 v117, v115, v116
	s_waitcnt lgkmcnt(7)
	v_add_f32_e32 v102, v106, v107
	s_waitcnt lgkmcnt(6)
	v_add_f32_e32 v98, v98, v99
	ds_bpermute_b32 v103, v115, v102
	ds_bpermute_b32 v99, v115, v98
	s_waitcnt lgkmcnt(7)
	v_add_f32_e32 v90, v90, v91
	s_waitcnt lgkmcnt(6)
	v_add_f32_e32 v68, v82, v83
	ds_bpermute_b32 v91, v115, v90
	ds_bpermute_b32 v69, v115, v68
	s_waitcnt lgkmcnt(7)
	v_add_f32_e32 v70, v74, v75
	s_waitcnt lgkmcnt(6)
	v_add_f32_e32 v66, v66, v67
	ds_bpermute_b32 v71, v115, v70
	ds_bpermute_b32 v67, v115, v66
	s_waitcnt lgkmcnt(7)
	v_add_f32_e32 v100, v118, v119
	s_waitcnt lgkmcnt(6)
	v_add_f32_e32 v101, v116, v117
	v_max3_f32 v92, v100, 0, v101
	s_waitcnt lgkmcnt(5)
	v_add_f32_e32 v93, v102, v103
	s_waitcnt lgkmcnt(4)
	v_add_f32_e32 v94, v98, v99
	v_max3_f32 v92, v92, v93, v94
	s_waitcnt lgkmcnt(3)
	v_add_f32_e32 v72, v90, v91
	s_waitcnt lgkmcnt(2)
	v_add_f32_e32 v68, v68, v69
	v_max3_f32 v68, v92, v72, v68
	s_waitcnt lgkmcnt(1)
	v_add_f32_e32 v69, v70, v71
	s_waitcnt lgkmcnt(0)
	v_add_f32_e32 v66, v66, v67
	v_xor_b32_e32 v114, 4, v132
	v_max3_f32 v66, v68, v69, v66
	ds_bpermute_b32 v68, v114, v66
	v_xor_b32_e32 v67, 8, v132
	s_cmp_gt_u32 s56, 11
	s_cselect_b64 s[50:51], -1, 0
	s_cmp_lt_u32 s56, 12
	s_waitcnt lgkmcnt(0)
	v_max_f32_e32 v68, v68, v68
	v_max_f32_e32 v69, v66, v68
	ds_bpermute_b32 v70, v67, v69
	v_xor_b32_e32 v68, 16, v132
	s_cselect_b64 vcc, -1, 0
	s_lshl_b32 s2, s48, 8
	s_add_i32 s6, s2, s76
	s_waitcnt lgkmcnt(0)
	v_max_f32_e32 v70, v70, v70
	v_max_f32_e32 v70, v69, v70
	ds_bpermute_b32 v71, v68, v70
	v_xor_b32_e32 v69, 32, v132
	s_lshl_b32 s39, s56, 2
	s_ashr_i32 s18, s6, 13
	s_and_b32 s39, s39, 12
	s_waitcnt lgkmcnt(0)
	v_max_f32_e32 v71, v71, v71
	v_max_f32_e32 v70, v70, v71
	ds_bpermute_b32 v71, v69, v70
	v_cndmask_b32_e32 v66, 1.0, v254, vcc
	v_cmp_eq_u32_e64 s[6:7], 0, v131
	s_or_b32 s41, s39, s68
	s_lshl_b32 s39, s18, 5
	s_and_saveexec_b64 s[48:49], s[6:7]
	s_cbranch_execz .LBB0_336
	s_mov_b64 s[54:55], -1
	s_and_b64 vcc, exec, s[50:51]
	s_cbranch_vccz .LBB0_330
	s_lshl_b32 s52, s41, 1
	s_or_b32 s52, s39, s52
	s_mov_b64 s[54:55], 0
